# nt hint on read-once streaming loads (x rows, scan inputs, residual bases, attention Q and merge loads)
# baseline (speedup 1.0000x reference)
.LBB0_103:
	s_cmpk_lt_i32 s30, 0x4000
	s_cbranch_scc0 .LBB0_108
	s_load_dwordx2 s[4:5], s[0:1], 0x10
	s_load_dwordx2 s[6:7], s[0:1], 0x0
	s_lshl_b32 s8, s30, 1
	v_lshlrev_b32_e32 v30, 4, v243
	s_ashr_i32 s9, s8, 31
	s_waitcnt lgkmcnt(0)
	global_load_dwordx4 v[2:5], v30, s[4:5] offset:3072
	global_load_dwordx4 v[6:9], v30, s[4:5] offset:2048
	global_load_dwordx4 v[10:13], v30, s[4:5] offset:1024
	global_load_dwordx4 v[14:17], v30, s[4:5]
	s_lshl_b64 s[4:5], s[8:9], 12
	s_add_u32 s4, s6, s4
	v_mov_b32_e32 v31, 0
	s_addc_u32 s5, s7, s5
	v_lshl_add_u64 v[18:19], s[4:5], 0, v[30:31]
	s_movk_i32 s10, 0x1000
	v_add_co_u32_e32 v32, vcc, s10, v18
	v_mbcnt_lo_u32_b32 v1, -1, 0
	s_nop 0
	v_addc_co_u32_e32 v33, vcc, 0, v19, vcc
	global_load_dwordx4 v[74:77], v30, s[4:5] nt
	global_load_dwordx4 v[66:69], v30, s[4:5] offset:1024 nt
	global_load_dwordx4 v[78:81], v[32:33], off nt
	global_load_dwordx4 v[70:73], v[32:33], off offset:1024 nt
	global_load_dwordx4 v[26:29], v30, s[4:5] offset:2048 nt
	global_load_dwordx4 v[18:21], v30, s[4:5] offset:3072 nt
	global_load_dwordx4 v[42:45], v[32:33], off offset:2048 nt
	global_load_dwordx4 v[22:25], v[32:33], off offset:3072 nt
	v_lshl_add_u64 v[84:85], s[6:7], 0, v[30:31]
	v_mbcnt_hi_u32_b32 v30, -1, v1
	v_and_b32_e32 v1, 64, v30
	v_add_u32_e32 v31, 64, v1
	v_xor_b32_e32 v1, 1, v30
	v_cmp_lt_i32_e32 vcc, v1, v31
	v_xor_b32_e32 v32, 2, v30
	s_lshl_b64 s[4:5], s[8:9], 11
	v_cndmask_b32_e32 v1, v30, v1, vcc
	v_cmp_lt_i32_e32 vcc, v32, v31
	s_lshl_b32 s10, s52, 4
	s_ashr_i32 s11, s10, 31
	v_cndmask_b32_e32 v32, v30, v32, vcc
	v_lshlrev_b32_e32 v88, 2, v32
	v_xor_b32_e32 v32, 4, v30
	v_cmp_lt_i32_e32 vcc, v32, v31
	v_lshlrev_b32_e32 v1, 2, v1
	s_lshl_b64 s[12:13], s[10:11], 11
	v_cndmask_b32_e32 v32, v30, v32, vcc
	v_lshlrev_b32_e32 v89, 2, v32
	v_xor_b32_e32 v32, 8, v30
	v_cmp_lt_i32_e32 vcc, v32, v31
	v_mov_b32_e32 v93, 0x358637bd
	s_mov_b32 s11, 0xf800000
	v_cndmask_b32_e32 v32, v30, v32, vcc
	v_lshlrev_b32_e32 v90, 2, v32
	v_xor_b32_e32 v32, 16, v30
	v_cmp_lt_i32_e32 vcc, v32, v31
	v_mov_b32_e32 v94, 0x260
	s_nop 0
	v_cndmask_b32_e32 v32, v30, v32, vcc
	v_lshlrev_b32_e32 v91, 2, v32
	v_xor_b32_e32 v32, 32, v30
	v_cmp_lt_i32_e32 vcc, v32, v31
	v_mov_b32_e32 v31, s5
	s_nop 0
	v_cndmask_b32_e32 v30, v30, v32, vcc
	v_lshlrev_b32_e32 v92, 2, v30
	v_lshl_or_b32 v30, v243, 3, s4
	v_lshl_add_u64 v[30:31], v[82:83], 0, v[30:31]
	s_mov_b64 s[4:5], 0x4000000
	v_lshl_add_u64 v[86:87], v[30:31], 0, s[4:5]
	s_branch .LBB0_106

.LBB0_106:
	s_add_i32 s8, s8, s10
	s_cmpk_gt_i32 s8, 0x7fff
	s_cselect_b64 s[14:15], -1, 0
	s_and_b64 vcc, exec, s[14:15]
	s_cbranch_vccnz .LBB0_105
	s_ashr_i32 s9, s8, 31
	s_lshl_b64 s[4:5], s[8:9], 12
	v_lshl_add_u64 v[96:97], v[84:85], 0, s[4:5]
	v_add_co_u32_e32 v98, vcc, 0x1000, v96
	s_nop 1
	v_addc_co_u32_e32 v99, vcc, 0, v97, vcc
	global_load_dwordx4 v[30:33], v[96:97], off nt
	global_load_dwordx4 v[46:49], v[96:97], off offset:1024 nt
	global_load_dwordx4 v[38:41], v[98:99], off nt
	global_load_dwordx4 v[34:37], v[98:99], off offset:1024 nt
	global_load_dwordx4 v[58:61], v[96:97], off offset:2048 nt
	global_load_dwordx4 v[62:65], v[96:97], off offset:3072 nt
	global_load_dwordx4 v[54:57], v[98:99], off offset:2048 nt
	global_load_dwordx4 v[50:53], v[98:99], off offset:3072 nt
	s_branch .LBB0_105

.LBB0_327:
	s_or_b64 exec, exec, s[12:13]
	s_waitcnt lgkmcnt(0)
	s_add_u32 s10, s6, 0xc000000
	s_addc_u32 s11, s7, 0
	s_cmpk_lt_i32 s2, 0x800
	v_and_b32_e32 v8, 15, v164
	v_ashrrev_i32_e32 v7, 4, v164
	s_cselect_b64 s[4:5], -1, 0
	s_and_b64 vcc, exec, s[4:5]
	v_lshlrev_b32_e32 v165, 2, v7
	v_lshlrev_b32_e32 v2, 4, v8
	s_cbranch_vccz .LBB0_343
	s_lshl_b32 s8, s2, 4
	s_and_b32 s9, s8, 0x3f80
	s_and_b32 s8, s8, 0xffffff80
	v_add3_u32 v4, s8, -3, v165
	s_lshl_b32 s8, s28, 8
	v_mov_b32_e32 v3, 0
	s_add_u32 s8, s10, s8
	v_mov_b32_e32 v34, v3
	v_mov_b32_e32 v35, v3
	v_ashrrev_i32_e32 v5, 31, v4
	v_add_u32_e32 v9, s9, v165
	s_addc_u32 s9, s11, 0
	v_mov_b32_e32 v32, v3
	v_mov_b32_e32 v33, v3
	v_mov_b64_e32 v[38:39], v[34:35]
	v_lshl_add_u64 v[0:1], s[8:9], 0, v[2:3]
	v_cmp_lt_i32_e32 vcc, 2, v9
	v_lshlrev_b64 v[4:5], 11, v[4:5]
	v_mov_b64_e32 v[36:37], v[32:33]
	s_and_saveexec_b64 s[8:9], vcc
	s_cbranch_execz .LBB0_330
	v_lshl_add_u64 v[10:11], v[0:1], 0, v[4:5]
	global_load_dwordx4 v[36:39], v[10:11], off nt
.LBB0_330:
	s_or_b64 exec, exec, s[8:9]
	v_cmp_lt_i32_e32 vcc, 1, v9
	s_and_saveexec_b64 s[8:9], vcc
	s_cbranch_execz .LBB0_332
	v_lshl_add_u64 v[10:11], v[0:1], 0, v[4:5]
	global_load_dwordx4 v[32:35], v[10:11], off offset:2048 nt
.LBB0_332:
	s_or_b64 exec, exec, s[8:9]
	v_mov_b32_e32 v40, 0
	v_mov_b32_e32 v42, v40
	v_mov_b32_e32 v43, v40
	v_mov_b32_e32 v41, v40
	v_mov_b64_e32 v[46:47], v[42:43]
	v_cmp_lt_i32_e32 vcc, 0, v9
	v_mov_b64_e32 v[44:45], v[40:41]
	s_and_saveexec_b64 s[8:9], vcc
	s_cbranch_execz .LBB0_334
	v_lshl_add_u64 v[10:11], v[0:1], 0, v[4:5]
	v_add_co_u32_e32 v10, vcc, 0x1000, v10
	s_nop 1
	v_addc_co_u32_e32 v11, vcc, 0, v11, vcc
	global_load_dwordx4 v[44:47], v[10:11], off nt
.LBB0_334:
	s_or_b64 exec, exec, s[8:9]
	v_cmp_lt_i32_e32 vcc, -1, v9
	s_and_saveexec_b64 s[8:9], vcc
	s_cbranch_execz .LBB0_336
	v_lshl_add_u64 v[10:11], v[0:1], 0, v[4:5]
	v_add_co_u32_e32 v10, vcc, 0x1000, v10
	s_nop 1
	v_addc_co_u32_e32 v11, vcc, 0, v11, vcc
	global_load_dwordx4 v[40:43], v[10:11], off offset:2048 nt
.LBB0_336:
	s_or_b64 exec, exec, s[8:9]
	v_mov_b32_e32 v48, 0
	v_mov_b32_e32 v50, v48
	v_mov_b32_e32 v51, v48
	v_mov_b32_e32 v49, v48
	v_mov_b64_e32 v[54:55], v[50:51]
	v_cmp_lt_i32_e32 vcc, -2, v9
	v_mov_b64_e32 v[52:53], v[48:49]
	s_and_saveexec_b64 s[8:9], vcc
	s_cbranch_execz .LBB0_338
	v_lshl_add_u64 v[10:11], v[0:1], 0, v[4:5]
	v_add_co_u32_e32 v10, vcc, 0x2000, v10
	s_nop 1
	v_addc_co_u32_e32 v11, vcc, 0, v11, vcc
	global_load_dwordx4 v[52:55], v[10:11], off nt
.LBB0_338:
	s_or_b64 exec, exec, s[8:9]
	v_cmp_lt_i32_e32 vcc, -3, v9
	s_and_saveexec_b64 s[8:9], vcc
	s_cbranch_execz .LBB0_340
	v_lshl_add_u64 v[10:11], v[0:1], 0, v[4:5]
	v_add_co_u32_e32 v10, vcc, 0x2000, v10
	s_nop 1
	v_addc_co_u32_e32 v11, vcc, 0, v11, vcc
	global_load_dwordx4 v[48:51], v[10:11], off offset:2048 nt
.LBB0_340:
	s_or_b64 exec, exec, s[8:9]
	v_cmp_lt_i32_e32 vcc, -4, v9
	v_mov_b32_e32 v59, 0
	v_mov_b32_e32 v58, 0
	v_mov_b32_e32 v57, 0
	v_mov_b32_e32 v56, 0
	s_and_saveexec_b64 s[8:9], vcc
	s_cbranch_execz .LBB0_342
	v_lshl_add_u64 v[0:1], v[0:1], 0, v[4:5]
	v_add_co_u32_e32 v0, vcc, 0x3000, v0
	s_nop 1
	v_addc_co_u32_e32 v1, vcc, 0, v1, vcc
	global_load_dwordx4 v[56:59], v[0:1], off nt

.LBB0_347:
	s_add_i32 s48, s6, s52
	s_cmpk_gt_i32 s48, 0x7ff
	s_cselect_b64 s[30:31], -1, 0
	s_and_b64 vcc, exec, s[30:31]
	v_mov_b32_e32 v31, v59
	v_mov_b32_e32 v30, v58
	v_mov_b32_e32 v29, v57
	v_mov_b32_e32 v28, v56
	s_cbranch_vccnz .LBB0_363
	s_lshl_b32 s4, s48, 4
	s_and_b32 s5, s4, 0x3f80
	s_and_b32 s4, s4, 0xffffff80
	v_add_u32_e32 v2, s4, v166
	v_ashrrev_i32_e32 v3, 31, v2
	v_mov_b32_e32 v6, v0
	v_mov_b32_e32 v7, v0
	v_add_u32_e32 v28, s5, v165
	v_mov_b32_e32 v4, v0
	v_mov_b32_e32 v5, v0
	v_lshlrev_b64 v[2:3], 11, v[2:3]
	v_mov_b64_e32 v[10:11], v[6:7]
	v_cmp_lt_i32_e32 vcc, 2, v28
	v_lshl_add_u64 v[60:61], v[126:127], 0, v[2:3]
	v_mov_b64_e32 v[8:9], v[4:5]
	s_and_saveexec_b64 s[4:5], vcc
	s_cbranch_execz .LBB0_350
	global_load_dwordx4 v[8:11], v[60:61], off nt
.LBB0_350:
	s_or_b64 exec, exec, s[4:5]
	v_cmp_lt_i32_e32 vcc, 1, v28
	s_and_saveexec_b64 s[4:5], vcc
	s_cbranch_execz .LBB0_352
	global_load_dwordx4 v[4:7], v[60:61], off offset:2048 nt
.LBB0_352:
	s_or_b64 exec, exec, s[4:5]
	v_mov_b32_e32 v2, v0
	v_mov_b32_e32 v3, v0
	v_mov_b32_e32 v1, v0
	v_mov_b64_e32 v[14:15], v[2:3]
	v_cmp_lt_i32_e32 vcc, 0, v28
	v_mov_b64_e32 v[12:13], v[0:1]
	s_and_saveexec_b64 s[4:5], vcc
	s_cbranch_execz .LBB0_354
	v_add_co_u32_e32 v12, vcc, 0x1000, v60
	s_nop 1
	v_addc_co_u32_e32 v13, vcc, 0, v61, vcc
	global_load_dwordx4 v[12:15], v[12:13], off nt
.LBB0_354:
	s_or_b64 exec, exec, s[4:5]
	v_mov_b64_e32 v[18:19], v[2:3]
	v_cmp_lt_i32_e32 vcc, -1, v28
	v_mov_b64_e32 v[16:17], v[0:1]
	s_and_saveexec_b64 s[4:5], vcc
	s_cbranch_execz .LBB0_356
	v_add_co_u32_e32 v2, vcc, 0x1000, v60
	s_nop 1
	v_addc_co_u32_e32 v3, vcc, 0, v61, vcc
	global_load_dwordx4 v[16:19], v[2:3], off offset:2048 nt
.LBB0_356:
	s_or_b64 exec, exec, s[4:5]
	v_mov_b32_e32 v2, v0
	v_mov_b32_e32 v3, v0
	v_mov_b32_e32 v1, v0
	v_mov_b64_e32 v[22:23], v[2:3]
	v_cmp_lt_i32_e32 vcc, -2, v28
	v_mov_b64_e32 v[20:21], v[0:1]
	s_and_saveexec_b64 s[4:5], vcc
	s_cbranch_execz .LBB0_358
	v_add_co_u32_e32 v20, vcc, 0x2000, v60
	s_nop 1
	v_addc_co_u32_e32 v21, vcc, 0, v61, vcc
	global_load_dwordx4 v[20:23], v[20:21], off nt
.LBB0_358:
	s_or_b64 exec, exec, s[4:5]
	v_mov_b64_e32 v[26:27], v[2:3]
	v_cmp_lt_i32_e32 vcc, -3, v28
	v_mov_b64_e32 v[24:25], v[0:1]
	s_and_saveexec_b64 s[4:5], vcc
	s_cbranch_execz .LBB0_360
	v_add_co_u32_e32 v2, vcc, 0x2000, v60
	s_nop 1
	v_addc_co_u32_e32 v3, vcc, 0, v61, vcc
	global_load_dwordx4 v[24:27], v[2:3], off offset:2048 nt
.LBB0_360:
	s_or_b64 exec, exec, s[4:5]
	v_cmp_lt_i32_e32 vcc, -4, v28
	v_mov_b32_e32 v31, 0
	v_mov_b32_e32 v30, 0
	v_mov_b32_e32 v29, 0
	v_mov_b32_e32 v28, 0
	s_and_saveexec_b64 s[4:5], vcc
	s_cbranch_execz .LBB0_362
	v_add_co_u32_e32 v2, vcc, 0x3000, v60
	s_nop 1
	v_addc_co_u32_e32 v3, vcc, 0, v61, vcc
	global_load_dwordx4 v[28:31], v[2:3], off nt

.LBB0_363:
	v_lshlrev_b32_e32 v87, 16, v32
	v_and_b32_e32 v89, 0xffff0000, v32
	v_lshlrev_b32_e32 v91, 16, v33
	v_and_b32_e32 v93, 0xffff0000, v33
	v_lshlrev_b32_e32 v94, 16, v38
	v_and_b32_e32 v96, 0xffff0000, v38
	v_lshlrev_b32_e32 v98, 16, v39
	v_and_b32_e32 v100, 0xffff0000, v39
	v_lshlrev_b32_e32 v103, 16, v40
	v_and_b32_e32 v105, 0xffff0000, v40
	v_lshlrev_b32_e32 v107, 16, v41
	v_and_b32_e32 v109, 0xffff0000, v41
	v_lshlrev_b32_e32 v114, 16, v47
	v_and_b32_e32 v116, 0xffff0000, v47
	v_lshlrev_b32_e32 v40, 16, v53
	v_lshlrev_b32_e32 v41, 16, v49
	v_and_b32_e32 v39, 0xffff0000, v49
	v_and_b32_e32 v38, 0xffff0000, v53
	v_lshlrev_b32_e32 v32, 16, v55
	v_lshlrev_b32_e32 v33, 16, v51
	v_and_b32_e32 v3, 0xffff0000, v51
	v_and_b32_e32 v2, 0xffff0000, v55
	v_lshlrev_b32_e32 v65, 16, v56
	v_and_b32_e32 v63, 0xffff0000, v56
	v_lshlrev_b32_e32 v61, 16, v57
	v_and_b32_e32 v55, 0xffff0000, v57
	v_lshlrev_b32_e32 v53, 16, v58
	v_and_b32_e32 v51, 0xffff0000, v58
	v_lshlrev_b32_e32 v49, 16, v59
	v_and_b32_e32 v47, 0xffff0000, v59
	ds_read_b128 v[56:59], v168
	ds_read_b128 v[66:69], v168 offset:512
	ds_read_b128 v[70:73], v167
	ds_read_b128 v[74:77], v167 offset:16
	ds_read_b128 v[78:81], v168 offset:16
	ds_read_b128 v[82:85], v168 offset:528
	v_and_b32_e32 v88, 0xffff0000, v36
	s_waitcnt lgkmcnt(4)
	v_mov_b32_e32 v119, v66
	v_mov_b32_e32 v66, v57
	v_mov_b32_e32 v118, v56
	v_pk_mul_f32 v[56:57], v[66:67], v[88:89]
	v_lshlrev_b32_e32 v110, 16, v46
	v_and_b32_e32 v112, 0xffff0000, v46
	s_waitcnt lgkmcnt(3)
	v_add_f32_e32 v46, v71, v56
	v_and_b32_e32 v92, 0xffff0000, v37
	v_add_f32_e32 v46, v46, v57
	v_mov_b32_e32 v57, v68
	v_mov_b32_e32 v68, v59
	v_mov_b32_e32 v56, v58
	v_pk_mul_f32 v[58:59], v[68:69], v[92:93]
	v_lshlrev_b32_e32 v90, 16, v37
	v_lshlrev_b32_e32 v99, 16, v35
	v_and_b32_e32 v101, 0xffff0000, v35
	v_lshlrev_b32_e32 v37, 16, v50
	v_and_b32_e32 v35, 0xffff0000, v50
	v_add_f32_e32 v50, v73, v58
	v_and_b32_e32 v97, 0xffff0000, v34
	v_add_f32_e32 v50, v50, v59
	s_waitcnt lgkmcnt(0)
	v_mov_b32_e32 v59, v82
	v_mov_b32_e32 v82, v79
	v_mov_b32_e32 v58, v78
	v_pk_mul_f32 v[78:79], v[82:83], v[96:97]
	v_lshlrev_b32_e32 v86, 16, v36
	v_lshlrev_b32_e32 v95, 16, v34
	v_lshlrev_b32_e32 v36, 16, v54
	v_and_b32_e32 v34, 0xffff0000, v54
	v_add_f32_e32 v54, v75, v78
	v_add_f32_e32 v54, v54, v79
	v_mov_b32_e32 v79, v84
	v_mov_b32_e32 v84, v81
	v_mov_b32_e32 v78, v80
	v_pk_mul_f32 v[80:81], v[84:85], v[100:101]
	v_lshlrev_b32_e32 v102, 16, v44
	v_add_f32_e32 v62, v77, v80
	v_pk_mul_f32 v[120:121], v[118:119], v[86:87]
	v_add_f32_e32 v62, v62, v81
	v_pk_mov_b32 v[80:81], v[86:87], v[102:103] op_sel:[1,0]
	v_add_f32_e32 v1, v70, v120
	v_pk_mul_f32 v[80:81], v[118:119], v[80:81]
	v_and_b32_e32 v104, 0xffff0000, v44
	v_add_f32_e32 v1, v1, v121
	v_pk_mul_f32 v[120:121], v[56:57], v[90:91]
	v_add_f32_e32 v64, v70, v80
	v_lshlrev_b32_e32 v106, 16, v45
	v_and_b32_e32 v108, 0xffff0000, v45
	v_lshlrev_b32_e32 v115, 16, v43
	v_and_b32_e32 v117, 0xffff0000, v43
	v_lshlrev_b32_e32 v45, 16, v48
	v_and_b32_e32 v43, 0xffff0000, v48
	v_add_f32_e32 v48, v72, v120
	v_add_f32_e32 v64, v64, v81
	v_pk_mov_b32 v[80:81], v[88:89], v[104:105] op_sel:[1,0]
	v_add_f32_e32 v48, v48, v121
	v_pk_mul_f32 v[120:121], v[58:59], v[94:95]
	v_pk_mul_f32 v[80:81], v[66:67], v[80:81]
	v_lshlrev_b32_e32 v111, 16, v42
	v_and_b32_e32 v113, 0xffff0000, v42
	v_lshlrev_b32_e32 v44, 16, v52
	v_and_b32_e32 v42, 0xffff0000, v52
	v_add_f32_e32 v52, v74, v120
	v_add_f32_e32 v80, v71, v80
	v_add_f32_e32 v52, v52, v121
	v_pk_mul_f32 v[120:121], v[78:79], v[98:99]
	v_add_f32_e32 v98, v80, v81
	v_pk_mov_b32 v[80:81], v[90:91], v[106:107] op_sel:[1,0]
	v_add_f32_e32 v60, v76, v120
	v_pk_mul_f32 v[80:81], v[56:57], v[80:81]
	v_add_f32_e32 v60, v60, v121
	v_add_f32_e32 v80, v72, v80
	v_add_f32_e32 v120, v80, v81
	v_pk_mov_b32 v[80:81], v[92:93], v[108:109] op_sel:[1,0]
	v_pk_mov_b32 v[88:89], v[106:107], v[40:41] op_sel:[1,0]
	v_pk_mul_f32 v[80:81], v[68:69], v[80:81]
	v_pk_mov_b32 v[90:91], v[108:109], v[38:39] op_sel:[1,0]
	v_add_f32_e32 v80, v73, v80
	v_add_f32_e32 v121, v80, v81
	v_pk_mov_b32 v[80:81], v[94:95], v[110:111] op_sel:[1,0]
	v_pk_mov_b32 v[92:93], v[110:111], v[36:37] op_sel:[1,0]
	v_pk_mul_f32 v[80:81], v[58:59], v[80:81]
	v_pk_mov_b32 v[94:95], v[112:113], v[34:35] op_sel:[1,0]
	v_add_f32_e32 v80, v74, v80
	v_add_f32_e32 v122, v80, v81
	v_pk_mov_b32 v[80:81], v[96:97], v[112:113] op_sel:[1,0]
	s_bfe_u32 s5, s6, 0x70003
	v_pk_mul_f32 v[80:81], v[82:83], v[80:81]
	s_ashr_i32 s7, s6, 10
	v_add_f32_e32 v80, v75, v80
	v_add_f32_e32 v123, v80, v81
	v_pk_mov_b32 v[80:81], v[98:99], v[114:115] op_sel:[1,0]
	s_lshl_b32 s8, s5, 7
	v_pk_mul_f32 v[80:81], v[78:79], v[80:81]
	s_lshl_b32 s9, s7, 14
	v_add_f32_e32 v80, v76, v80
	v_add_f32_e32 v99, v80, v81
	v_pk_mov_b32 v[80:81], v[100:101], v[116:117] op_sel:[1,0]
	s_or_b32 s8, s8, s9
	v_pk_mul_f32 v[80:81], v[84:85], v[80:81]
	s_lshr_b32 s4, s6, 3
	v_add_f32_e32 v80, v77, v80
	v_add_f32_e32 v100, v80, v81
	v_pk_mul_f32 v[80:81], v[118:119], v[102:103]
	s_nop 0
	v_add_f32_e32 v80, v70, v80
	v_add_f32_e32 v101, v80, v81
	v_pk_mul_f32 v[80:81], v[66:67], v[104:105]
	s_nop 0
	v_add_f32_e32 v80, v71, v80
	v_add_f32_e32 v157, v80, v81
	v_pk_mul_f32 v[80:81], v[56:57], v[106:107]
	v_pk_mul_f32 v[56:57], v[56:57], v[88:89]
	v_add_f32_e32 v80, v72, v80
	v_add_f32_e32 v158, v80, v81
	v_pk_mul_f32 v[80:81], v[68:69], v[108:109]
	v_add_f32_e32 v56, v72, v56
	v_add_f32_e32 v80, v73, v80
	v_add_f32_e32 v159, v80, v81
	v_pk_mul_f32 v[80:81], v[58:59], v[110:111]
	v_add_f32_e32 v187, v56, v57
	v_add_f32_e32 v80, v74, v80
	v_add_f32_e32 v160, v80, v81
	v_pk_mul_f32 v[80:81], v[82:83], v[112:113]
	v_pk_mul_f32 v[56:57], v[68:69], v[90:91]
	v_add_f32_e32 v80, v75, v80
	v_add_f32_e32 v161, v80, v81
	v_pk_mul_f32 v[80:81], v[78:79], v[114:115]
	v_add_f32_e32 v56, v73, v56
	v_add_f32_e32 v80, v76, v80
	v_add_f32_e32 v162, v80, v81
	v_pk_mul_f32 v[80:81], v[84:85], v[116:117]
	v_add_f32_e32 v188, v56, v57
	v_add_f32_e32 v80, v77, v80
	v_add_f32_e32 v163, v80, v81
	v_pk_mov_b32 v[80:81], v[102:103], v[44:45] op_sel:[1,0]
	v_pk_mul_f32 v[56:57], v[58:59], v[92:93]
	v_pk_mul_f32 v[86:87], v[118:119], v[80:81]
	v_add_f32_e32 v56, v74, v56
	v_add_f32_e32 v70, v70, v86
	v_add_f32_e32 v189, v56, v57
	v_pk_mul_f32 v[56:57], v[82:83], v[94:95]
	v_add_f32_e32 v118, v70, v87
	v_pk_mov_b32 v[86:87], v[104:105], v[42:43] op_sel:[1,0]
	v_add_f32_e32 v56, v75, v56
	v_pk_mov_b32 v[82:83], v[114:115], v[32:33] op_sel:[1,0]
	v_pk_mul_f32 v[66:67], v[66:67], v[86:87]
	v_add_f32_e32 v190, v56, v57
	v_pk_mul_f32 v[56:57], v[78:79], v[82:83]
	v_add_f32_e32 v66, v71, v66
	v_add_f32_e32 v56, v76, v56
	v_add_f32_e32 v119, v66, v67
	v_add_f32_e32 v191, v56, v57
	ds_read_b128 v[56:59], v168 offset:1024
	ds_read_b128 v[66:69], v168 offset:1536
	v_pk_mov_b32 v[78:79], v[116:117], v[2:3] op_sel:[1,0]
	s_nop 0
	v_pk_mul_f32 v[70:71], v[84:85], v[78:79]
	s_waitcnt lgkmcnt(1)
	v_mov_b32_e32 v84, v56
	s_waitcnt lgkmcnt(0)
	v_mov_b32_e32 v85, v66
	v_mov_b32_e32 v66, v57
	v_add_f32_e32 v70, v77, v70
	v_pk_mul_f32 v[56:57], v[66:67], v[104:105]
	v_add_f32_e32 v192, v70, v71
	ds_read_b128 v[70:73], v168 offset:1040
	ds_read_b128 v[74:77], v168 offset:1552
	v_pk_mul_f32 v[96:97], v[84:85], v[102:103]
	v_add_f32_e32 v46, v46, v56
	v_add_f32_e32 v1, v1, v96
	v_add_f32_e32 v102, v46, v57
	v_mov_b32_e32 v56, v58
	v_mov_b32_e32 v57, v68
	v_add_f32_e32 v1, v1, v97
	v_pk_mul_f32 v[96:97], v[56:57], v[106:107]
	v_mov_b32_e32 v68, v59
	v_add_f32_e32 v46, v48, v96
	v_pk_mul_f32 v[58:59], v[68:69], v[108:109]
	v_add_f32_e32 v103, v46, v97
	v_add_f32_e32 v46, v50, v58
	v_add_f32_e32 v104, v46, v59
	s_waitcnt lgkmcnt(1)
	v_mov_b32_e32 v58, v70
	s_waitcnt lgkmcnt(0)
	v_mov_b32_e32 v59, v74
	v_pk_mul_f32 v[96:97], v[58:59], v[110:111]
	v_mov_b32_e32 v74, v71
	v_add_f32_e32 v46, v52, v96
	v_pk_mul_f32 v[70:71], v[74:75], v[112:113]
	v_add_f32_e32 v105, v46, v97
	v_add_f32_e32 v46, v54, v70
	v_add_f32_e32 v106, v46, v71
	v_mov_b32_e32 v70, v72
	v_mov_b32_e32 v71, v76
	v_pk_mul_f32 v[96:97], v[70:71], v[114:115]
	v_mov_b32_e32 v76, v73
	v_add_f32_e32 v46, v60, v96
	v_pk_mul_f32 v[72:73], v[76:77], v[116:117]
	v_add_f32_e32 v96, v46, v97
	v_add_f32_e32 v46, v62, v72
	v_add_f32_e32 v97, v46, v73
	v_pk_mul_f32 v[72:73], v[84:85], v[80:81]
	v_mov_b32_e32 v62, v43
	v_add_f32_e32 v46, v64, v72
	v_add_f32_e32 v80, v46, v73
	v_pk_mul_f32 v[72:73], v[66:67], v[86:87]
	v_mov_b32_e32 v64, v45
	v_add_f32_e32 v46, v98, v72
	v_add_f32_e32 v81, v46, v73
	v_pk_mul_f32 v[72:73], v[56:57], v[88:89]
	v_mov_b32_e32 v60, v41
	v_add_f32_e32 v46, v120, v72
	v_add_f32_e32 v86, v46, v73
	v_pk_mul_f32 v[72:73], v[68:69], v[90:91]
	v_mov_b32_e32 v54, v39
	v_add_f32_e32 v46, v121, v72
	v_add_f32_e32 v87, v46, v73
	v_pk_mul_f32 v[72:73], v[58:59], v[92:93]
	v_mov_b32_e32 v52, v37
	v_add_f32_e32 v46, v122, v72
	v_add_f32_e32 v88, v46, v73
	v_pk_mul_f32 v[72:73], v[74:75], v[94:95]
	v_mov_b32_e32 v50, v35
	v_add_f32_e32 v46, v123, v72
	v_add_f32_e32 v89, v46, v73
	v_pk_mul_f32 v[72:73], v[70:71], v[82:83]
	v_mov_b32_e32 v48, v33
	v_add_f32_e32 v46, v99, v72
	v_add_f32_e32 v82, v46, v73
	v_pk_mul_f32 v[72:73], v[76:77], v[78:79]
	s_nop 0
	v_add_f32_e32 v46, v100, v72
	v_add_f32_e32 v78, v46, v73
	v_pk_mul_f32 v[72:73], v[84:85], v[44:45]
	v_mov_b32_e32 v46, v3
	v_add_f32_e32 v44, v101, v72
	v_add_f32_e32 v79, v44, v73
	v_pk_mul_f32 v[72:73], v[66:67], v[42:43]
	v_pk_mul_f32 v[44:45], v[84:85], v[64:65]
	v_add_f32_e32 v42, v157, v72
	v_add_f32_e32 v83, v42, v73
	v_pk_mul_f32 v[72:73], v[56:57], v[40:41]
	v_pk_mul_f32 v[42:43], v[66:67], v[62:63]
	v_add_f32_e32 v40, v158, v72
	v_add_f32_e32 v90, v40, v73
	v_pk_mul_f32 v[72:73], v[68:69], v[38:39]
	v_pk_mul_f32 v[40:41], v[56:57], v[60:61]
	v_add_f32_e32 v38, v159, v72
	v_add_f32_e32 v91, v38, v73
	v_pk_mul_f32 v[72:73], v[58:59], v[36:37]
	v_pk_mul_f32 v[38:39], v[68:69], v[54:55]
	v_add_f32_e32 v36, v160, v72
	v_add_f32_e32 v92, v36, v73
	v_pk_mul_f32 v[72:73], v[74:75], v[34:35]
	v_pk_mul_f32 v[36:37], v[58:59], v[52:53]
	v_add_f32_e32 v34, v161, v72
	v_add_f32_e32 v93, v34, v73
	v_pk_mul_f32 v[72:73], v[70:71], v[32:33]
	v_pk_mul_f32 v[34:35], v[74:75], v[50:51]
	v_add_f32_e32 v32, v162, v72
	v_add_f32_e32 v94, v32, v73
	v_pk_mul_f32 v[72:73], v[76:77], v[2:3]
	v_pk_mul_f32 v[32:33], v[70:71], v[48:49]
	v_add_f32_e32 v2, v163, v72
	v_add_f32_e32 v72, v2, v73
	v_add_f32_e32 v2, v118, v44
	v_add_f32_e32 v44, v2, v45
	v_add_f32_e32 v2, v119, v42
	v_add_f32_e32 v42, v2, v43
	v_add_f32_e32 v2, v187, v40
	v_add_f32_e32 v40, v2, v41
	v_add_f32_e32 v2, v188, v38
	v_add_f32_e32 v38, v2, v39
	v_add_f32_e32 v2, v189, v36
	v_add_f32_e32 v36, v2, v37
	v_add_f32_e32 v2, v190, v34
	v_add_f32_e32 v37, v2, v35
	v_add_f32_e32 v2, v191, v32
	v_add_f32_e32 v39, v2, v33
	v_cvt_pk_bf16_f32 v32, v1, v102
	v_cvt_pk_bf16_f32 v33, v103, v104
	v_cvt_pk_bf16_f32 v34, v105, v106
	v_cvt_pk_bf16_f32 v35, v96, v97
	v_pk_mul_f32 v[2:3], v[76:77], v[46:47]
	ds_write_b128 v184, v[32:35]
	v_cvt_pk_bf16_f32 v32, v80, v81
	v_cvt_pk_bf16_f32 v33, v86, v87
	v_cvt_pk_bf16_f32 v34, v88, v89
	v_cvt_pk_bf16_f32 v35, v82, v78
	v_add_f32_e32 v2, v192, v2
	ds_write_b128 v184, v[32:35] offset:272
	v_cvt_pk_bf16_f32 v32, v79, v83
	v_cvt_pk_bf16_f32 v33, v90, v91
	v_cvt_pk_bf16_f32 v34, v92, v93
	v_cvt_pk_bf16_f32 v35, v94, v72
	v_add_f32_e32 v2, v2, v3
	ds_write_b128 v184, v[32:35] offset:544
	v_cvt_pk_bf16_f32 v32, v44, v42
	v_cvt_pk_bf16_f32 v33, v40, v38
	v_cvt_pk_bf16_f32 v34, v36, v37
	v_cvt_pk_bf16_f32 v35, v39, v2
	ds_write_b128 v184, v[32:35] offset:816
	global_load_dwordx4 v[32:35], v[124:125], off
	global_load_dwordx4 v[36:39], v[132:133], off
	global_load_dwordx4 v[40:43], v[134:135], off
	global_load_dwordx4 v[44:47], v[136:137], off
	global_load_dwordx4 v[48:51], v[124:125], off offset:64
	global_load_dwordx4 v[52:55], v[138:139], off
	global_load_dwordx4 v[56:59], v[140:141], off
	global_load_dwordx4 v[60:63], v[142:143], off
	global_load_dwordx4 v[64:67], v[144:145], off
	global_load_dwordx4 v[68:71], v[146:147], off
	global_load_dwordx4 v[72:75], v[124:125], off offset:128
	global_load_dwordx4 v[80:83], v[124:125], off offset:192
	global_load_dwordx4 v[84:87], v[148:149], off
	global_load_dwordx4 v[92:95], v[150:151], off
	global_load_dwordx4 v[188:191], v[152:153], off
	global_load_dwordx4 v[76:79], v[154:155], off
	s_waitcnt lgkmcnt(0)
	s_barrier
	ds_read_b128 v[88:91], v185
	ds_read_b128 v[96:99], v169
	ds_read_b128 v[100:103], v169 offset:64
	ds_read_b128 v[104:107], v185 offset:64
	ds_read_b128 v[112:115], v170
	ds_read_b128 v[116:119], v170 offset:64
	ds_read_b128 v[192:195], v185 offset:4352
	ds_read_b128 v[196:199], v185 offset:4416
	ds_read_b128 v[212:215], v185 offset:8704
	ds_read_b128 v[216:219], v185 offset:8768
	ds_read_b128 v[232:235], v185 offset:13056
	ds_read_b128 v[236:239], v185 offset:13120
	s_waitcnt vmcnt(15) lgkmcnt(10)
	v_mfma_f32_16x16x32_bf16 v[108:111], v[32:35], v[88:91], v[96:99]
	v_add_u32_e32 v2, s8, v165
	v_ashrrev_i32_e32 v3, 31, v2
	v_lshlrev_b64 v[162:163], 11, v[2:3]
	s_waitcnt vmcnt(14) lgkmcnt(7)
	v_mfma_f32_16x16x32_bf16 v[120:123], v[36:39], v[88:91], v[112:115]
	v_add_u32_e32 v1, 0x1000, v186
	s_waitcnt vmcnt(13)
	v_mfma_f32_16x16x32_bf16 v[158:161], v[40:43], v[88:91], v[100:103]
	s_waitcnt vmcnt(12) lgkmcnt(6)
	v_mfma_f32_16x16x32_bf16 v[88:91], v[44:47], v[88:91], v[116:119]
	s_waitcnt lgkmcnt(5)
	v_mfma_f32_16x16x32_bf16 v[200:203], v[32:35], v[192:195], v[96:99]
	v_mfma_f32_16x16x32_bf16 v[204:207], v[36:39], v[192:195], v[112:115]
	v_mfma_f32_16x16x32_bf16 v[208:211], v[40:43], v[192:195], v[100:103]
	v_mfma_f32_16x16x32_bf16 v[192:195], v[44:47], v[192:195], v[116:119]
	s_waitcnt lgkmcnt(3)
	v_mfma_f32_16x16x32_bf16 v[220:223], v[32:35], v[212:215], v[96:99]
	v_mfma_f32_16x16x32_bf16 v[224:227], v[36:39], v[212:215], v[112:115]
	s_waitcnt lgkmcnt(1)
	v_mfma_f32_16x16x32_bf16 v[32:35], v[32:35], v[232:235], v[96:99]
	v_mfma_f32_16x16x32_bf16 v[36:39], v[36:39], v[232:235], v[112:115]
	v_mfma_f32_16x16x32_bf16 v[228:231], v[40:43], v[212:215], v[100:103]
	v_mfma_f32_16x16x32_bf16 v[212:215], v[44:47], v[212:215], v[116:119]
	v_mfma_f32_16x16x32_bf16 v[40:43], v[40:43], v[232:235], v[100:103]
	v_mfma_f32_16x16x32_bf16 v[44:47], v[44:47], v[232:235], v[116:119]
	s_waitcnt vmcnt(11)
	v_mfma_f32_16x16x32_bf16 v[96:99], v[48:51], v[104:107], v[108:111]
	s_waitcnt vmcnt(10)
	v_mfma_f32_16x16x32_bf16 v[100:103], v[52:55], v[104:107], v[120:123]
	s_waitcnt vmcnt(9)
	v_mfma_f32_16x16x32_bf16 v[108:111], v[56:59], v[104:107], v[158:161]
	s_waitcnt vmcnt(8)
	v_mfma_f32_16x16x32_bf16 v[88:91], v[60:63], v[104:107], v[88:91]
	v_mfma_f32_16x16x32_bf16 v[104:107], v[48:51], v[196:199], v[200:203]
	v_mfma_f32_16x16x32_bf16 v[112:115], v[52:55], v[196:199], v[204:207]
	v_mfma_f32_16x16x32_bf16 v[120:123], v[60:63], v[196:199], v[192:195]
	v_mfma_f32_16x16x32_bf16 v[158:161], v[48:51], v[216:219], v[220:223]
	v_mfma_f32_16x16x32_bf16 v[192:195], v[52:55], v[216:219], v[224:227]
	s_waitcnt lgkmcnt(0)
	v_mfma_f32_16x16x32_bf16 v[32:35], v[48:51], v[236:239], v[32:35]
	v_mfma_f32_16x16x32_bf16 v[36:39], v[52:55], v[236:239], v[36:39]
	ds_read_b128 v[48:51], v185 offset:128
	ds_read_b128 v[52:55], v185 offset:192
	v_mfma_f32_16x16x32_bf16 v[116:119], v[56:59], v[196:199], v[208:211]
	v_mfma_f32_16x16x32_bf16 v[196:199], v[56:59], v[216:219], v[228:231]
	v_mfma_f32_16x16x32_bf16 v[200:203], v[60:63], v[216:219], v[212:215]
	v_mfma_f32_16x16x32_bf16 v[40:43], v[56:59], v[236:239], v[40:43]
	v_mfma_f32_16x16x32_bf16 v[44:47], v[60:63], v[236:239], v[44:47]
	s_waitcnt vmcnt(5) lgkmcnt(1)
	v_mfma_f32_16x16x32_bf16 v[56:59], v[72:75], v[48:51], v[96:99]
	v_mfma_f32_16x16x32_bf16 v[60:63], v[64:67], v[48:51], v[100:103]
	v_mfma_f32_16x16x32_bf16 v[108:111], v[68:71], v[48:51], v[108:111]
	s_waitcnt vmcnt(3)
	v_mfma_f32_16x16x32_bf16 v[48:51], v[84:87], v[48:51], v[88:91]
	s_nop 2
	ds_read_b128 v[88:91], v185 offset:4480
	ds_read_b128 v[204:207], v185 offset:4544
	s_waitcnt lgkmcnt(1)
	v_mfma_f32_16x16x32_bf16 v[104:107], v[72:75], v[88:91], v[104:107]
	v_mfma_f32_16x16x32_bf16 v[112:115], v[64:67], v[88:91], v[112:115]
	v_mfma_f32_16x16x32_bf16 v[116:119], v[68:71], v[88:91], v[116:119]
	v_mfma_f32_16x16x32_bf16 v[120:123], v[84:87], v[88:91], v[120:123]
	ds_read_b128 v[88:91], v185 offset:8832
	ds_read_b128 v[208:211], v185 offset:8896
	s_waitcnt lgkmcnt(1)
	v_mfma_f32_16x16x32_bf16 v[158:161], v[72:75], v[88:91], v[158:161]
	v_mfma_f32_16x16x32_bf16 v[192:195], v[64:67], v[88:91], v[192:195]
	v_mfma_f32_16x16x32_bf16 v[196:199], v[68:71], v[88:91], v[196:199]
	v_mfma_f32_16x16x32_bf16 v[200:203], v[84:87], v[88:91], v[200:203]
	ds_read_b128 v[88:91], v185 offset:13184
	ds_read_b128 v[96:99], v185 offset:13248
	s_waitcnt lgkmcnt(1)
	v_mfma_f32_16x16x32_bf16 v[64:67], v[64:67], v[88:91], v[36:39]
	s_nop 2
	v_or_b32_e32 v38, 1, v2
	v_ashrrev_i32_e32 v39, 31, v38
	v_mfma_f32_16x16x32_bf16 v[32:35], v[72:75], v[88:91], v[32:35]
	v_lshl_add_u64 v[36:37], v[128:129], 0, v[162:163]
	v_mfma_f32_16x16x32_bf16 v[212:215], v[68:71], v[88:91], v[40:43]
	s_waitcnt vmcnt(0)
	v_mfma_f32_16x16x32_bf16 v[68:71], v[76:79], v[204:207], v[120:123]
	v_mfma_f32_16x16x32_bf16 v[120:123], v[80:83], v[208:211], v[158:161]
	s_nop 2
	v_lshlrev_b64 v[160:161], 11, v[38:39]
	v_mfma_f32_16x16x32_bf16 v[100:103], v[84:87], v[88:91], v[44:47]
	v_lshl_add_u64 v[38:39], v[128:129], 0, v[160:161]
	s_nop 1
	global_load_dwordx4 v[44:47], v[36:37], off nt
	global_load_dwordx4 v[40:43], v[38:39], off nt
	v_or_b32_e32 v36, 2, v2
	v_or_b32_e32 v2, 3, v2
	v_ashrrev_i32_e32 v37, 31, v36
	v_ashrrev_i32_e32 v3, 31, v2
	v_mfma_f32_16x16x32_bf16 v[216:219], v[80:83], v[52:55], v[56:59]
	v_lshlrev_b64 v[158:159], 11, v[36:37]
	v_lshlrev_b64 v[2:3], 11, v[2:3]
	v_lshl_add_u64 v[36:37], v[128:129], 0, v[158:159]
	v_mfma_f32_16x16x32_bf16 v[88:91], v[188:191], v[52:55], v[108:111]
	v_exp_f32_e32 v70, v70
	s_nop 2
	v_exp_f32_e32 v187, v217
	s_waitcnt lgkmcnt(0)
	v_mfma_f32_16x16x32_bf16 v[108:111], v[80:83], v[96:99], v[32:35]
	s_nop 2
	v_lshl_add_u64 v[32:33], v[128:129], 0, v[2:3]
	v_mfma_f32_16x16x32_bf16 v[224:227], v[80:83], v[204:207], v[104:107]
	global_load_dwordx4 v[36:39], v[36:37], off nt
	s_nop 0
	global_load_dwordx4 v[32:35], v[32:33], off nt
	ds_read2_b64 v[80:83], v1 offset0:32 offset1:36
	v_add_u32_e32 v1, 0x2000, v186
	v_mfma_f32_16x16x32_bf16 v[104:107], v[92:95], v[96:99], v[64:67]
	s_nop 2
	ds_read2_b64 v[64:67], v1 offset0:64 offset1:68
	v_add_u32_e32 v1, 0x3000, v186
	v_mfma_f32_16x16x32_bf16 v[84:87], v[76:79], v[52:55], v[48:51]
	s_nop 2
	ds_read2_b64 v[48:51], v1 offset0:96 offset1:100
	v_exp_f32_e32 v1, v216
	v_mfma_f32_16x16x32_bf16 v[220:223], v[92:95], v[52:55], v[60:63]
	s_nop 1
	v_exp_f32_e32 v86, v86
	v_add_f32_e32 v1, 1.0, v1
	v_mfma_f32_16x16x32_bf16 v[228:231], v[92:95], v[204:207], v[112:115]
	v_rcp_f32_e32 v1, v1
	s_nop 1
	v_exp_f32_e32 v157, v220
	v_mfma_f32_16x16x32_bf16 v[72:75], v[188:191], v[204:207], v[116:119]
	v_add_f32_e32 v157, 1.0, v157
	v_mfma_f32_16x16x32_bf16 v[116:119], v[92:95], v[208:211], v[192:195]
	ds_read2_b64 v[92:95], v186 offset1:4
	s_waitcnt lgkmcnt(0)
	s_barrier
	ds_read_b128 v[112:115], v174
	v_mfma_f32_16x16x32_bf16 v[60:63], v[188:191], v[208:211], v[196:199]
	s_waitcnt lgkmcnt(1)
	v_lshlrev_b32_e32 v194, 16, v92
	v_and_b32_e32 v195, 0xffff0000, v92
	v_exp_f32_e32 v92, v222
	s_waitcnt lgkmcnt(0)
	v_mul_f32_e32 v1, v1, v112
	v_mfma_f32_16x16x32_bf16 v[52:55], v[188:191], v[96:99], v[212:215]
	v_exp_f32_e32 v188, v1
	v_add_f32_e32 v1, 1.0, v187
	v_rcp_f32_e32 v1, v1
	v_exp_f32_e32 v187, v221
	v_rcp_f32_e32 v190, v157
	v_fma_f32 v157, -v188, v188, 1.0
	v_mul_f32_e32 v1, v1, v113
	v_exp_f32_e32 v189, v1
	v_add_f32_e32 v1, 1.0, v187
	v_rcp_f32_e32 v191, v1
	v_max_f32_e32 v157, 0, v157
	v_fma_f32 v1, -v189, v189, 1.0
	v_max_f32_e32 v1, 0, v1
	v_sqrt_f32_e32 v193, v1
	v_exp_f32_e32 v1, v218
	v_sqrt_f32_e32 v192, v157
	v_exp_f32_e32 v157, v219
	v_add_f32_e32 v92, 1.0, v92
	v_add_f32_e32 v1, 1.0, v1
	v_rcp_f32_e32 v1, v1
	v_pk_mul_f32 v[192:193], v[190:191], v[192:193]
	v_rcp_f32_e32 v196, v92
	v_pk_mul_f32 v[192:193], v[192:193], v[194:195]
	v_mul_f32_e32 v1, v1, v114
	v_exp_f32_e32 v190, v1
	v_add_f32_e32 v1, 1.0, v157
	v_rcp_f32_e32 v1, v1
	v_exp_f32_e32 v157, v223
	v_fma_f32 v92, -v190, v190, 1.0
	v_max_f32_e32 v92, 0, v92
	v_mul_f32_e32 v1, v1, v115
	v_exp_f32_e32 v191, v1
	v_add_f32_e32 v1, 1.0, v157
	v_rcp_f32_e32 v197, v1
	v_sqrt_f32_e32 v198, v92
	v_fma_f32 v1, -v191, v191, 1.0
	v_max_f32_e32 v1, 0, v1
	v_sqrt_f32_e32 v199, v1
	v_lshlrev_b32_e32 v92, 16, v93
	v_and_b32_e32 v93, 0xffff0000, v93
	v_add_u32_e32 v1, 0, v175
	v_pk_mul_f32 v[194:195], v[196:197], v[198:199]
	ds_write_b128 v1, v[188:191]
	v_pk_mul_f32 v[194:195], v[194:195], v[92:93]
	v_exp_f32_e32 v92, v224
	v_exp_f32_e32 v93, v228
	v_add_u32_e32 v1, s47, v175
	ds_write_b128 v1, v[192:195]
	v_add_f32_e32 v92, 1.0, v92
	v_rcp_f32_e32 v92, v92
	v_add_f32_e32 v1, 1.0, v93
	v_exp_f32_e32 v93, v225
	v_exp_f32_e32 v157, v229
	v_mul_f32_e32 v92, v92, v112
	v_exp_f32_e32 v188, v92
	v_rcp_f32_e32 v92, v1
	v_add_f32_e32 v1, 1.0, v93
	v_rcp_f32_e32 v1, v1
	v_fma_f32 v93, -v188, v188, 1.0
	v_max_f32_e32 v93, 0, v93
	v_sqrt_f32_e32 v190, v93
	v_mul_f32_e32 v1, v1, v113
	v_exp_f32_e32 v189, v1
	v_add_f32_e32 v1, 1.0, v157
	v_rcp_f32_e32 v93, v1
	v_exp_f32_e32 v157, v227
	v_fma_f32 v1, -v189, v189, 1.0
	v_max_f32_e32 v1, 0, v1
	v_sqrt_f32_e32 v191, v1
	v_exp_f32_e32 v1, v226
	v_lshlrev_b32_e32 v192, 16, v80
	v_and_b32_e32 v193, 0xffff0000, v80
	v_pk_mul_f32 v[92:93], v[92:93], v[190:191]
	v_add_f32_e32 v1, 1.0, v1
	v_rcp_f32_e32 v1, v1
	v_exp_f32_e32 v80, v230
	v_pk_mul_f32 v[192:193], v[92:93], v[192:193]
	v_mfma_f32_16x16x32_bf16 v[56:59], v[76:79], v[208:211], v[200:203]
	v_mul_f32_e32 v1, v1, v114
	v_exp_f32_e32 v190, v1
	v_add_f32_e32 v1, 1.0, v157
	v_rcp_f32_e32 v1, v1
	v_exp_f32_e32 v157, v231
	v_add_f32_e32 v80, 1.0, v80
	v_rcp_f32_e32 v194, v80
	v_mul_f32_e32 v1, v1, v115
	v_exp_f32_e32 v191, v1
	v_add_f32_e32 v1, 1.0, v157
	v_fma_f32 v80, -v190, v190, 1.0
	v_rcp_f32_e32 v195, v1
	v_fma_f32 v1, -v191, v191, 1.0
	v_max_f32_e32 v80, 0, v80
	v_max_f32_e32 v1, 0, v1
	v_sqrt_f32_e32 v196, v80
	v_sqrt_f32_e32 v197, v1
	v_lshlrev_b32_e32 v80, 16, v81
	v_and_b32_e32 v81, 0xffff0000, v81
	v_add_u32_e32 v1, 0, v176
	v_pk_mul_f32 v[92:93], v[194:195], v[196:197]
	ds_write_b128 v1, v[188:191]
	v_pk_mul_f32 v[194:195], v[92:93], v[80:81]
	v_exp_f32_e32 v80, v120
	v_exp_f32_e32 v81, v116
	v_add_u32_e32 v1, s47, v176
	ds_write_b128 v1, v[192:195]
	v_add_f32_e32 v80, 1.0, v80
	v_rcp_f32_e32 v80, v80
	v_add_f32_e32 v1, 1.0, v81
	v_exp_f32_e32 v81, v121
	v_exp_f32_e32 v93, v117
	v_mul_f32_e32 v80, v80, v112
	v_exp_f32_e32 v116, v80
	v_rcp_f32_e32 v80, v1
	v_add_f32_e32 v1, 1.0, v81
	v_rcp_f32_e32 v1, v1
	v_fma_f32 v81, -v116, v116, 1.0
	v_max_f32_e32 v81, 0, v81
	v_sqrt_f32_e32 v92, v81
	v_mul_f32_e32 v1, v1, v113
	v_exp_f32_e32 v117, v1
	v_add_f32_e32 v1, 1.0, v93
	v_rcp_f32_e32 v81, v1
	v_lshlrev_b32_e32 v120, 16, v64
	v_fma_f32 v1, -v117, v117, 1.0
	v_max_f32_e32 v1, 0, v1
	v_sqrt_f32_e32 v93, v1
	v_exp_f32_e32 v1, v122
	v_and_b32_e32 v121, 0xffff0000, v64
	v_exp_f32_e32 v64, v118
	v_pk_mul_f32 v[80:81], v[80:81], v[92:93]
	v_add_f32_e32 v1, 1.0, v1
	v_rcp_f32_e32 v1, v1
	v_exp_f32_e32 v93, v123
	v_add_f32_e32 v64, 1.0, v64
	v_rcp_f32_e32 v92, v64
	v_mul_f32_e32 v1, v1, v114
	v_exp_f32_e32 v118, v1
	v_add_f32_e32 v1, 1.0, v93
	v_rcp_f32_e32 v1, v1
	v_exp_f32_e32 v93, v119
	v_fma_f32 v64, -v118, v118, 1.0
	v_max_f32_e32 v64, 0, v64
	v_mul_f32_e32 v1, v1, v115
	v_exp_f32_e32 v119, v1
	v_add_f32_e32 v1, 1.0, v93
	v_rcp_f32_e32 v93, v1
	v_sqrt_f32_e32 v122, v64
	v_fma_f32 v1, -v119, v119, 1.0
	v_max_f32_e32 v1, 0, v1
	v_sqrt_f32_e32 v123, v1
	v_pk_mul_f32 v[120:121], v[80:81], v[120:121]
	v_lshlrev_b32_e32 v64, 16, v65
	v_and_b32_e32 v65, 0xffff0000, v65
	v_pk_mul_f32 v[80:81], v[92:93], v[122:123]
	v_add_u32_e32 v1, 0, v177
	v_pk_mul_f32 v[122:123], v[80:81], v[64:65]
	v_exp_f32_e32 v64, v108
	v_exp_f32_e32 v65, v104
	ds_write_b128 v1, v[116:119]
	v_add_u32_e32 v1, s47, v177
	v_add_f32_e32 v64, 1.0, v64
	v_rcp_f32_e32 v64, v64
	ds_write_b128 v1, v[120:123]
	v_add_f32_e32 v1, 1.0, v65
	v_exp_f32_e32 v65, v109
	v_mul_f32_e32 v64, v64, v112
	v_exp_f32_e32 v104, v64
	v_rcp_f32_e32 v64, v1
	v_add_f32_e32 v1, 1.0, v65
	v_rcp_f32_e32 v1, v1
	v_exp_f32_e32 v81, v105
	v_fma_f32 v65, -v104, v104, 1.0
	v_max_f32_e32 v65, 0, v65
	v_mul_f32_e32 v1, v1, v113
	v_exp_f32_e32 v105, v1
	v_add_f32_e32 v1, 1.0, v81
	v_sqrt_f32_e32 v80, v65
	v_rcp_f32_e32 v65, v1
	v_fma_f32 v1, -v105, v105, 1.0
	v_max_f32_e32 v1, 0, v1
	v_sqrt_f32_e32 v81, v1
	v_exp_f32_e32 v1, v110
	v_lshlrev_b32_e32 v92, 16, v48
	v_and_b32_e32 v93, 0xffff0000, v48
	v_pk_mul_f32 v[64:65], v[64:65], v[80:81]
	v_add_f32_e32 v1, 1.0, v1
	v_rcp_f32_e32 v1, v1
	v_exp_f32_e32 v81, v111
	v_exp_f32_e32 v48, v106
	v_pk_mul_f32 v[108:109], v[64:65], v[92:93]
	v_mul_f32_e32 v1, v1, v114
	v_exp_f32_e32 v106, v1
	v_add_f32_e32 v1, 1.0, v81
	v_rcp_f32_e32 v1, v1
	v_exp_f32_e32 v81, v107
	v_add_f32_e32 v48, 1.0, v48
	v_rcp_f32_e32 v80, v48
	v_mul_f32_e32 v1, v1, v115
	v_exp_f32_e32 v107, v1
	v_add_f32_e32 v1, 1.0, v81
	v_fma_f32 v48, -v106, v106, 1.0
	v_rcp_f32_e32 v81, v1
	v_fma_f32 v1, -v107, v107, 1.0
	v_max_f32_e32 v48, 0, v48
	v_max_f32_e32 v1, 0, v1
	v_sqrt_f32_e32 v110, v48
	v_sqrt_f32_e32 v111, v1
	v_lshlrev_b32_e32 v48, 16, v49
	v_and_b32_e32 v49, 0xffff0000, v49
	v_add_u32_e32 v1, 0, v178
	v_pk_mul_f32 v[64:65], v[80:81], v[110:111]
	ds_write_b128 v1, v[104:107]
	v_pk_mul_f32 v[110:111], v[64:65], v[48:49]
	v_exp_f32_e32 v48, v88
	v_add_u32_e32 v1, s47, v178
	ds_write_b128 v1, v[108:111]
	ds_read_b128 v[104:107], v179
	v_add_f32_e32 v48, 1.0, v48
	v_exp_f32_e32 v1, v84
	v_rcp_f32_e32 v48, v48
	v_exp_f32_e32 v49, v89
	v_exp_f32_e32 v65, v85
	v_add_f32_e32 v1, 1.0, v1
	s_waitcnt lgkmcnt(0)
	v_mul_f32_e32 v48, v48, v104
	v_exp_f32_e32 v84, v48
	v_rcp_f32_e32 v48, v1
	v_add_f32_e32 v1, 1.0, v49
	v_rcp_f32_e32 v1, v1
	v_fma_f32 v49, -v84, v84, 1.0
	v_max_f32_e32 v49, 0, v49
	v_sqrt_f32_e32 v64, v49
	v_mul_f32_e32 v1, v1, v105
	v_exp_f32_e32 v85, v1
	v_add_f32_e32 v1, 1.0, v65
	v_rcp_f32_e32 v49, v1
	v_exp_f32_e32 v88, v87
	v_fma_f32 v1, -v85, v85, 1.0
	v_max_f32_e32 v1, 0, v1
	v_sqrt_f32_e32 v65, v1
	v_exp_f32_e32 v1, v90
	v_lshlrev_b32_e32 v80, 16, v94
	v_and_b32_e32 v81, 0xffff0000, v94
	v_pk_mul_f32 v[48:49], v[48:49], v[64:65]
	v_add_f32_e32 v1, 1.0, v1
	v_rcp_f32_e32 v1, v1
	v_exp_f32_e32 v65, v91
	v_add_f32_e32 v64, 1.0, v86
	v_rcp_f32_e32 v64, v64
	v_mul_f32_e32 v1, v1, v106
	v_exp_f32_e32 v86, v1
	v_add_f32_e32 v1, 1.0, v65
	v_rcp_f32_e32 v1, v1
	v_exp_f32_e32 v58, v58
	v_fma_f32 v65, -v86, v86, 1.0
	v_max_f32_e32 v65, 0, v65
	v_mul_f32_e32 v1, v1, v107
	v_exp_f32_e32 v87, v1
	v_add_f32_e32 v1, 1.0, v88
	v_sqrt_f32_e32 v90, v65
	v_rcp_f32_e32 v65, v1
	v_fma_f32 v1, -v87, v87, 1.0
	v_max_f32_e32 v1, 0, v1
	v_sqrt_f32_e32 v91, v1
	v_pk_mul_f32 v[88:89], v[48:49], v[80:81]
	v_lshlrev_b32_e32 v48, 16, v95
	v_and_b32_e32 v49, 0xffff0000, v95
	v_pk_mul_f32 v[64:65], v[64:65], v[90:91]
	v_add_u32_e32 v1, 0, v180
	v_pk_mul_f32 v[90:91], v[64:65], v[48:49]
	v_exp_f32_e32 v48, v72
	v_exp_f32_e32 v49, v68
	ds_write_b128 v1, v[84:87]
	v_add_u32_e32 v1, s47, v180
	v_add_f32_e32 v48, 1.0, v48
	v_rcp_f32_e32 v48, v48
	ds_write_b128 v1, v[88:91]
	v_add_f32_e32 v1, 1.0, v49
	v_exp_f32_e32 v49, v73
	v_mul_f32_e32 v48, v48, v104
	v_exp_f32_e32 v68, v48
	v_rcp_f32_e32 v48, v1
	v_add_f32_e32 v1, 1.0, v49
	v_rcp_f32_e32 v1, v1
	v_exp_f32_e32 v65, v69
	v_fma_f32 v49, -v68, v68, 1.0
	v_max_f32_e32 v49, 0, v49
	v_mul_f32_e32 v1, v1, v105
	v_exp_f32_e32 v69, v1
	v_add_f32_e32 v1, 1.0, v65
	v_sqrt_f32_e32 v64, v49
	v_rcp_f32_e32 v49, v1
	v_fma_f32 v1, -v69, v69, 1.0
	v_max_f32_e32 v1, 0, v1
	v_sqrt_f32_e32 v65, v1
	v_exp_f32_e32 v1, v74
	v_lshlrev_b32_e32 v72, 16, v82
	v_and_b32_e32 v73, 0xffff0000, v82
	v_pk_mul_f32 v[48:49], v[48:49], v[64:65]
	v_add_f32_e32 v1, 1.0, v1
	v_rcp_f32_e32 v1, v1
	v_exp_f32_e32 v65, v75
	v_add_f32_e32 v64, 1.0, v70
	v_exp_f32_e32 v75, v71
	v_mul_f32_e32 v1, v1, v106
	v_exp_f32_e32 v70, v1
	v_add_f32_e32 v1, 1.0, v65
	v_rcp_f32_e32 v1, v1
	v_rcp_f32_e32 v64, v64
	v_fma_f32 v65, -v70, v70, 1.0
	v_max_f32_e32 v65, 0, v65
	v_mul_f32_e32 v1, v1, v107
	v_exp_f32_e32 v71, v1
	v_add_f32_e32 v1, 1.0, v75
	v_sqrt_f32_e32 v74, v65
	v_rcp_f32_e32 v65, v1
	v_fma_f32 v1, -v71, v71, 1.0
	v_max_f32_e32 v1, 0, v1
	v_sqrt_f32_e32 v75, v1
	v_pk_mul_f32 v[72:73], v[48:49], v[72:73]
	v_lshlrev_b32_e32 v48, 16, v83
	v_and_b32_e32 v49, 0xffff0000, v83
	v_pk_mul_f32 v[64:65], v[64:65], v[74:75]
	v_add_u32_e32 v1, 0, v181
	v_pk_mul_f32 v[74:75], v[64:65], v[48:49]
	v_exp_f32_e32 v48, v60
	v_exp_f32_e32 v49, v56
	ds_write_b128 v1, v[68:71]
	v_add_u32_e32 v1, s47, v181
	v_add_f32_e32 v48, 1.0, v48
	v_rcp_f32_e32 v48, v48
	ds_write_b128 v1, v[72:75]
	v_add_f32_e32 v1, 1.0, v49
	v_exp_f32_e32 v49, v61
	v_mul_f32_e32 v48, v48, v104
	v_exp_f32_e32 v56, v48
	v_rcp_f32_e32 v48, v1
	v_add_f32_e32 v1, 1.0, v49
	v_rcp_f32_e32 v1, v1
	v_exp_f32_e32 v61, v57
	v_fma_f32 v49, -v56, v56, 1.0
	v_max_f32_e32 v49, 0, v49
	v_mul_f32_e32 v1, v1, v105
	v_exp_f32_e32 v57, v1
	v_add_f32_e32 v1, 1.0, v61
	v_sqrt_f32_e32 v60, v49
	v_rcp_f32_e32 v49, v1
	v_fma_f32 v1, -v57, v57, 1.0
	v_max_f32_e32 v1, 0, v1
	v_sqrt_f32_e32 v61, v1
	v_exp_f32_e32 v1, v62
	v_mfma_f32_16x16x32_bf16 v[76:79], v[76:79], v[96:99], v[100:103]
	v_lshlrev_b32_e32 v64, 16, v66
	v_pk_mul_f32 v[48:49], v[48:49], v[60:61]
	v_add_f32_e32 v1, 1.0, v1
	v_rcp_f32_e32 v1, v1
	v_exp_f32_e32 v61, v63
	v_add_f32_e32 v60, 1.0, v58
	v_rcp_f32_e32 v62, v60
	v_mul_f32_e32 v1, v1, v106
	v_exp_f32_e32 v58, v1
	v_add_f32_e32 v1, 1.0, v61
	v_rcp_f32_e32 v1, v1
	v_exp_f32_e32 v61, v59
	v_fma_f32 v60, -v58, v58, 1.0
	v_max_f32_e32 v60, 0, v60
	v_mul_f32_e32 v1, v1, v107
	v_exp_f32_e32 v59, v1
	v_add_f32_e32 v1, 1.0, v61
	v_rcp_f32_e32 v63, v1
	v_sqrt_f32_e32 v68, v60
	v_fma_f32 v1, -v59, v59, 1.0
	v_max_f32_e32 v1, 0, v1
	v_sqrt_f32_e32 v69, v1
	v_and_b32_e32 v65, 0xffff0000, v66
	v_pk_mul_f32 v[60:61], v[48:49], v[64:65]
	v_lshlrev_b32_e32 v48, 16, v67
	v_and_b32_e32 v49, 0xffff0000, v67
	v_pk_mul_f32 v[62:63], v[62:63], v[68:69]
	v_add_u32_e32 v1, 0, v182
	v_pk_mul_f32 v[62:63], v[62:63], v[48:49]
	v_exp_f32_e32 v48, v52
	v_exp_f32_e32 v49, v76
	ds_write_b128 v1, v[56:59]
	v_add_u32_e32 v1, s47, v182
	v_add_f32_e32 v48, 1.0, v48
	v_rcp_f32_e32 v48, v48
	ds_write_b128 v1, v[60:63]
	v_add_f32_e32 v1, 1.0, v49
	v_exp_f32_e32 v49, v53
	v_mul_f32_e32 v48, v48, v104
	v_exp_f32_e32 v52, v48
	v_rcp_f32_e32 v48, v1
	v_add_f32_e32 v1, 1.0, v49
	v_rcp_f32_e32 v1, v1
	v_exp_f32_e32 v57, v77
	v_fma_f32 v49, -v52, v52, 1.0
	v_max_f32_e32 v49, 0, v49
	v_mul_f32_e32 v1, v1, v105
	v_exp_f32_e32 v53, v1
	v_add_f32_e32 v1, 1.0, v57
	v_sqrt_f32_e32 v56, v49
	v_rcp_f32_e32 v49, v1
	v_fma_f32 v1, -v53, v53, 1.0
	v_max_f32_e32 v1, 0, v1
	v_sqrt_f32_e32 v57, v1
	v_exp_f32_e32 v1, v54
	v_exp_f32_e32 v55, v55
	v_lshlrev_b32_e32 v58, 16, v50
	v_and_b32_e32 v59, 0xffff0000, v50
	v_add_f32_e32 v1, 1.0, v1
	v_rcp_f32_e32 v1, v1
	v_exp_f32_e32 v50, v78
	v_pk_mul_f32 v[48:49], v[48:49], v[56:57]
	v_exp_f32_e32 v57, v79
	v_mul_f32_e32 v1, v1, v106
	v_exp_f32_e32 v54, v1
	v_add_f32_e32 v1, 1.0, v55
	v_rcp_f32_e32 v1, v1
	v_add_f32_e32 v50, 1.0, v50
	v_rcp_f32_e32 v56, v50
	v_fma_f32 v50, -v54, v54, 1.0
	v_mul_f32_e32 v1, v1, v107
	v_exp_f32_e32 v55, v1
	v_add_f32_e32 v1, 1.0, v57
	v_rcp_f32_e32 v57, v1
	v_max_f32_e32 v50, 0, v50
	v_fma_f32 v1, -v55, v55, 1.0
	v_max_f32_e32 v1, 0, v1
	v_sqrt_f32_e32 v60, v50
	v_sqrt_f32_e32 v61, v1
	v_lshlrev_b32_e32 v50, 16, v51
	v_and_b32_e32 v51, 0xffff0000, v51
	v_add_u32_e32 v1, 0, v183
	v_pk_mul_f32 v[56:57], v[56:57], v[60:61]
	v_pk_mul_f32 v[48:49], v[48:49], v[58:59]
	v_pk_mul_f32 v[50:51], v[56:57], v[50:51]
	ds_write_b128 v1, v[52:55]
	v_add_u32_e32 v1, s47, v183
	ds_write_b128 v1, v[48:51]
	v_mov_b32_e32 v48, v164
	s_waitcnt lgkmcnt(0)
	s_barrier
	v_mov_b32_e32 v49, 0
	v_readfirstlane_b32 s9, v48
	s_ashr_i32 s8, s9, 7
	v_and_b32_e32 v1, 0x7f, v48
	s_mul_i32 s10, s8, 0x4200
	v_lshlrev_b32_e32 v48, 2, v1
	s_add_i32 s10, s10, 0
	v_add_u32_e32 v50, s10, v48
	v_mov_b32_e32 v51, 1.0
	s_movk_i32 s10, 0xbe00

.LBB0_474:
	s_lshl_b32 s19, s28, 8
	v_mov_b32_e32 v128, v204
	v_mov_b32_e32 v226, v205
	s_add_i32 s19, s19, s47
	s_nop 0
	v_add_u32_e32 v196, s19, v128
	s_lshl_b32 s19, s26, 8
	s_or_b32 s19, s19, s48
	v_lshl_add_u32 v192, v226, 3, s19
	v_ashrrev_i32_e32 v193, 31, v192
	v_ashrrev_i32_e32 v197, 31, v196
	v_lshl_add_u64 v[194:195], v[192:193], 2, s[10:11]
	v_lshlrev_b64 v[128:129], 12, v[196:197]
	v_add_u32_e32 v202, 16, v196
	v_add_u32_e32 v200, 32, v196
	v_add_u32_e32 v198, 48, v196
	v_lshl_add_u64 v[128:129], v[194:195], 0, v[128:129]
	v_ashrrev_i32_e32 v203, 31, v202
	v_ashrrev_i32_e32 v201, 31, v200
	v_ashrrev_i32_e32 v199, 31, v198
	global_load_dwordx4 v[210:213], v[128:129], off nt
	global_load_dwordx4 v[214:217], v[128:129], off offset:16 nt
	global_load_dwordx4 v[218:221], v[128:129], off offset:512 nt
	global_load_dwordx4 v[222:225], v[128:129], off offset:528 nt
	v_lshlrev_b64 v[128:129], 12, v[202:203]
	v_lshlrev_b64 v[130:131], 12, v[200:201]
	v_lshlrev_b64 v[132:133], 12, v[198:199]
	v_lshl_add_u64 v[128:129], v[194:195], 0, v[128:129]
	v_lshl_add_u64 v[130:131], v[194:195], 0, v[130:131]
	v_lshl_add_u64 v[132:133], v[194:195], 0, v[132:133]
	global_load_dwordx4 v[168:171], v[128:129], off offset:16 nt
	global_load_dwordx4 v[172:175], v[128:129], off nt
	global_load_dwordx4 v[160:163], v[128:129], off offset:528 nt
	global_load_dwordx4 v[164:167], v[128:129], off offset:512 nt
	global_load_dwordx4 v[152:155], v[130:131], off offset:16 nt
	global_load_dwordx4 v[156:159], v[130:131], off nt
	global_load_dwordx4 v[144:147], v[130:131], off offset:528 nt
	global_load_dwordx4 v[148:151], v[130:131], off offset:512 nt
	global_load_dwordx4 v[136:139], v[132:133], off offset:16 nt
	global_load_dwordx4 v[140:143], v[132:133], off nt
	s_nop 0
	global_load_dwordx4 v[128:131], v[132:133], off offset:528 nt
	s_nop 0
	global_load_dwordx4 v[132:135], v[132:133], off offset:512 nt
	v_cmp_eq_u32_e32 vcc, 0, v226
	v_lshlrev_b64 v[226:227], 11, v[196:197]
	v_lshl_add_u64 v[226:227], s[58:59], 0, v[226:227]
	v_lshl_add_u64 v[226:227], v[192:193], 1, v[226:227]
	s_waitcnt vmcnt(0)
	v_pk_add_f32 v[126:127], v[126:127], v[212:213]
	v_pk_add_f32 v[124:125], v[124:125], v[210:211]
	v_pk_add_f32 v[118:119], v[118:119], v[220:221]
	v_pk_add_f32 v[116:117], v[116:117], v[218:219]
	v_pk_add_f32 v[122:123], v[122:123], v[216:217]
	v_pk_add_f32 v[120:121], v[120:121], v[214:215]
	v_pk_add_f32 v[212:213], v[112:113], v[222:223]
	v_cvt_pk_bf16_f32 v112, v124, v125
	v_cvt_pk_bf16_f32 v113, v126, v127
	v_mul_f32_e32 v125, v125, v125
	v_mul_f32_e32 v127, v127, v127
	v_mul_f32_e32 v215, v117, v117
	v_mul_f32_e32 v216, v119, v119
	v_pk_add_f32 v[210:211], v[114:115], v[224:225]
	v_cvt_pk_bf16_f32 v114, v120, v121
	v_cvt_pk_bf16_f32 v115, v122, v123
	v_mul_f32_e32 v121, v121, v121
	v_mul_f32_e32 v217, v213, v213
	global_store_dwordx4 v[226:227], v[112:115], off
	v_fmac_f32_e32 v125, v124, v124
	v_fmac_f32_e32 v127, v126, v126
	v_cvt_pk_bf16_f32 v112, v116, v117
	v_cvt_pk_bf16_f32 v113, v118, v119
	v_fmac_f32_e32 v215, v116, v116
	v_fmac_f32_e32 v216, v118, v118
	v_mul_f32_e32 v123, v123, v123
	v_mul_f32_e32 v214, v211, v211
	v_cvt_pk_bf16_f32 v114, v212, v213
	v_cvt_pk_bf16_f32 v115, v210, v211
	v_fmac_f32_e32 v121, v120, v120
	v_fmac_f32_e32 v217, v212, v212
	global_store_dwordx4 v[226:227], v[112:115], off offset:256
	v_fmac_f32_e32 v123, v122, v122
	v_fmac_f32_e32 v214, v210, v210
	v_add_f32_e32 v112, v125, v127
	v_add_f32_e32 v113, v215, v216
	v_add_f32_e32 v112, v112, v121
	v_add_f32_e32 v113, v113, v217
	v_add_f32_e32 v112, v123, v112
	v_add_f32_e32 v113, v214, v113
	v_add_f32_e32 v112, v112, v113
	v_mov_b32_e32 v113, v112
	s_nop 1
	v_permlane16_swap_b32_e32 v112, v113
	v_add_f32_e32 v112, v112, v113
	v_mov_b32_e32 v113, v112
	s_nop 1
	v_permlane32_swap_b32_e32 v112, v113
	s_and_saveexec_b64 s[26:27], vcc
	s_cbranch_execz .LBB0_476
	v_lshl_add_u64 v[114:115], v[196:197], 2, s[8:9]
	v_add_f32_e32 v112, v112, v113
	global_atomic_add_f32 v[114:115], v112, off

.LBB0_482:
	s_or_b64 exec, exec, s[26:27]
	v_add_u32_e32 v118, 0x80, v196
	v_ashrrev_i32_e32 v119, 31, v118
	v_lshlrev_b64 v[64:65], 12, v[118:119]
	v_add_u32_e32 v116, 0x90, v196
	v_add_u32_e32 v114, 0xa0, v196
	v_add_u32_e32 v112, 0xb0, v196
	v_lshl_add_u64 v[64:65], v[194:195], 0, v[64:65]
	v_ashrrev_i32_e32 v117, 31, v116
	v_ashrrev_i32_e32 v115, 31, v114
	v_ashrrev_i32_e32 v113, 31, v112
	global_load_dwordx4 v[120:123], v[64:65], off nt
	global_load_dwordx4 v[124:127], v[64:65], off offset:16 nt
	global_load_dwordx4 v[128:131], v[64:65], off offset:512 nt
	global_load_dwordx4 v[132:135], v[64:65], off offset:528 nt
	v_lshlrev_b64 v[64:65], 12, v[116:117]
	v_lshlrev_b64 v[66:67], 12, v[114:115]
	v_lshlrev_b64 v[68:69], 12, v[112:113]
	v_lshl_add_u64 v[64:65], v[194:195], 0, v[64:65]
	v_lshl_add_u64 v[66:67], v[194:195], 0, v[66:67]
	v_lshl_add_u64 v[68:69], v[194:195], 0, v[68:69]
	global_load_dwordx4 v[104:107], v[64:65], off offset:16 nt
	global_load_dwordx4 v[108:111], v[64:65], off nt
	global_load_dwordx4 v[96:99], v[64:65], off offset:528 nt
	global_load_dwordx4 v[100:103], v[64:65], off offset:512 nt
	global_load_dwordx4 v[88:91], v[66:67], off offset:16 nt
	global_load_dwordx4 v[92:95], v[66:67], off nt
	global_load_dwordx4 v[80:83], v[66:67], off offset:528 nt
	global_load_dwordx4 v[84:87], v[66:67], off offset:512 nt
	global_load_dwordx4 v[72:75], v[68:69], off offset:16 nt
	global_load_dwordx4 v[76:79], v[68:69], off nt
	s_nop 0
	global_load_dwordx4 v[64:67], v[68:69], off offset:528 nt
	s_nop 0
	global_load_dwordx4 v[68:71], v[68:69], off offset:512 nt
	v_lshlrev_b64 v[136:137], 11, v[118:119]
	v_lshl_add_u64 v[136:137], s[58:59], 0, v[136:137]
	v_lshl_add_u64 v[136:137], v[192:193], 1, v[136:137]
	s_waitcnt vmcnt(15)
	v_pk_add_f32 v[62:63], v[62:63], v[122:123]
	v_pk_add_f32 v[60:61], v[60:61], v[120:121]
	s_waitcnt vmcnt(13)
	v_pk_add_f32 v[54:55], v[54:55], v[130:131]
	v_pk_add_f32 v[52:53], v[52:53], v[128:129]
	v_pk_add_f32 v[58:59], v[58:59], v[126:127]
	v_pk_add_f32 v[56:57], v[56:57], v[124:125]
	s_waitcnt vmcnt(12)
	v_pk_add_f32 v[122:123], v[48:49], v[132:133]
	v_cvt_pk_bf16_f32 v48, v60, v61
	v_cvt_pk_bf16_f32 v49, v62, v63
	v_mul_f32_e32 v61, v61, v61
	v_mul_f32_e32 v63, v63, v63
	v_mul_f32_e32 v125, v53, v53
	v_mul_f32_e32 v126, v55, v55
	v_pk_add_f32 v[120:121], v[50:51], v[134:135]
	v_cvt_pk_bf16_f32 v50, v56, v57
	v_cvt_pk_bf16_f32 v51, v58, v59
	v_mul_f32_e32 v57, v57, v57
	v_mul_f32_e32 v127, v123, v123
	global_store_dwordx4 v[136:137], v[48:51], off
	v_fmac_f32_e32 v61, v60, v60
	v_fmac_f32_e32 v63, v62, v62
	v_cvt_pk_bf16_f32 v48, v52, v53
	v_cvt_pk_bf16_f32 v49, v54, v55
	v_fmac_f32_e32 v125, v52, v52
	v_fmac_f32_e32 v126, v54, v54
	v_mul_f32_e32 v59, v59, v59
	v_mul_f32_e32 v124, v121, v121
	v_cvt_pk_bf16_f32 v50, v122, v123
	v_cvt_pk_bf16_f32 v51, v120, v121
	v_fmac_f32_e32 v57, v56, v56
	v_fmac_f32_e32 v127, v122, v122
	global_store_dwordx4 v[136:137], v[48:51], off offset:256
	v_fmac_f32_e32 v59, v58, v58
	v_fmac_f32_e32 v124, v120, v120
	v_add_f32_e32 v48, v61, v63
	v_add_f32_e32 v49, v125, v126
	v_add_f32_e32 v48, v48, v57
	v_add_f32_e32 v49, v49, v127
	v_add_f32_e32 v48, v59, v48
	v_add_f32_e32 v49, v124, v49
	v_add_f32_e32 v48, v48, v49
	v_mov_b32_e32 v49, v48
	s_nop 1
	v_permlane16_swap_b32_e32 v48, v49
	v_add_f32_e32 v48, v48, v49
	v_mov_b32_e32 v49, v48
	s_nop 1
	v_permlane32_swap_b32_e32 v48, v49
	s_and_saveexec_b64 s[26:27], vcc
	s_cbranch_execz .LBB0_484
	v_lshl_add_u64 v[50:51], v[118:119], 2, s[8:9]
	v_add_f32_e32 v48, v48, v49
	global_atomic_add_f32 v[50:51], v48, off

.LBB0_640:
	s_lshl_b32 s20, s50, 8
	v_mov_b32_e32 v120, v245
	v_mov_b32_e32 v250, v244
	s_add_i32 s20, s20, s36
	s_nop 0
	v_add_u32_e32 v236, s20, v120
	s_lshl_b32 s20, s49, 8
	s_or_b32 s20, s20, s37
	v_lshl_add_u32 v206, v250, 3, s20
	v_ashrrev_i32_e32 v207, 31, v206
	v_lshlrev_b64 v[238:239], 1, v[206:207]
	v_ashrrev_i32_e32 v237, 31, v236
	v_lshl_add_u64 v[124:125], s[58:59], 0, v[238:239]
	v_lshlrev_b64 v[240:241], 11, v[236:237]
	v_lshl_add_u64 v[120:121], v[124:125], 0, v[240:241]
	global_load_dwordx4 v[188:191], v[120:121], off nt
	global_load_dwordx4 v[184:187], v[120:121], off offset:256 nt
	v_add_u32_e32 v232, 16, v236
	v_ashrrev_i32_e32 v233, 31, v232
	v_add_u32_e32 v228, 32, v236
	v_lshlrev_b64 v[234:235], 11, v[232:233]
	v_ashrrev_i32_e32 v229, 31, v228
	v_add_u32_e32 v224, 48, v236
	v_lshl_add_u64 v[120:121], v[124:125], 0, v[234:235]
	v_lshlrev_b64 v[230:231], 11, v[228:229]
	v_ashrrev_i32_e32 v225, 31, v224
	v_add_u32_e32 v220, 0x80, v236
	global_load_dwordx4 v[180:183], v[120:121], off nt
	global_load_dwordx4 v[176:179], v[120:121], off offset:256 nt
	v_lshl_add_u64 v[120:121], v[124:125], 0, v[230:231]
	v_lshlrev_b64 v[226:227], 11, v[224:225]
	v_ashrrev_i32_e32 v221, 31, v220
	v_add_u32_e32 v216, 0x90, v236
	global_load_dwordx4 v[172:175], v[120:121], off nt
	global_load_dwordx4 v[168:171], v[120:121], off offset:256 nt
	v_lshl_add_u64 v[120:121], v[124:125], 0, v[226:227]
	v_lshlrev_b64 v[222:223], 11, v[220:221]
	v_ashrrev_i32_e32 v217, 31, v216
	v_add_u32_e32 v210, 0xa0, v236
	v_add_u32_e32 v208, 0xb0, v236
	global_load_dwordx4 v[164:167], v[120:121], off nt
	global_load_dwordx4 v[160:163], v[120:121], off offset:256 nt
	v_lshl_add_u64 v[120:121], v[124:125], 0, v[222:223]
	v_lshlrev_b64 v[218:219], 11, v[216:217]
	v_ashrrev_i32_e32 v211, 31, v210
	v_ashrrev_i32_e32 v209, 31, v208
	global_load_dwordx4 v[156:159], v[120:121], off nt
	global_load_dwordx4 v[152:155], v[120:121], off offset:256 nt
	v_lshl_add_u64 v[120:121], v[124:125], 0, v[218:219]
	v_lshlrev_b64 v[214:215], 11, v[210:211]
	v_lshlrev_b64 v[212:213], 11, v[208:209]
	global_load_dwordx4 v[148:151], v[120:121], off nt
	global_load_dwordx4 v[140:143], v[120:121], off offset:256 nt
	v_lshl_add_u64 v[120:121], v[124:125], 0, v[214:215]
	v_lshl_add_u64 v[124:125], v[124:125], 0, v[212:213]
	global_load_dwordx4 v[128:131], v[120:121], off nt
	s_nop 0
	global_load_dwordx4 v[120:123], v[120:121], off offset:256 nt
	s_nop 0
	global_load_dwordx4 v[132:135], v[124:125], off nt
	s_nop 0
	global_load_dwordx4 v[124:127], v[124:125], off offset:256 nt
	v_cmp_eq_u32_e32 vcc, 0, v250
	v_lshl_add_u64 v[240:241], s[58:59], 0, v[240:241]
	v_lshl_add_u64 v[238:239], v[240:241], 0, v[238:239]
	s_waitcnt vmcnt(0)
	v_lshlrev_b32_e32 v250, 16, v188
	v_and_b32_e32 v251, 0xffff0000, v188
	v_lshlrev_b32_e32 v188, 16, v189
	v_and_b32_e32 v189, 0xffff0000, v189
	v_lshlrev_b32_e32 v252, 16, v190
	v_and_b32_e32 v253, 0xffff0000, v190
	v_lshlrev_b32_e32 v190, 16, v191
	v_and_b32_e32 v191, 0xffff0000, v191
	v_pk_add_f32 v[146:147], v[146:147], v[188:189]
	v_pk_add_f32 v[144:145], v[144:145], v[250:251]
	v_pk_add_f32 v[188:189], v[138:139], v[190:191]
	v_pk_add_f32 v[190:191], v[136:137], v[252:253]
	v_cvt_pk_bf16_f32 v136, v144, v145
	v_cvt_pk_bf16_f32 v137, v146, v147
	s_nop 0
	v_cvt_pk_bf16_f32 v138, v190, v191
	v_cvt_pk_bf16_f32 v139, v188, v189
	global_store_dwordx4 v[238:239], v[136:139], off
	s_nop 1
	v_lshlrev_b32_e32 v136, 16, v184
	v_and_b32_e32 v137, 0xffff0000, v184
	v_lshlrev_b32_e32 v138, 16, v185
	v_and_b32_e32 v139, 0xffff0000, v185
	v_lshlrev_b32_e32 v184, 16, v186
	v_and_b32_e32 v185, 0xffff0000, v186
	v_lshlrev_b32_e32 v186, 16, v187
	v_and_b32_e32 v187, 0xffff0000, v187
	v_pk_add_f32 v[118:119], v[118:119], v[138:139]
	v_pk_add_f32 v[116:117], v[116:117], v[136:137]
	v_pk_add_f32 v[136:137], v[114:115], v[186:187]
	v_pk_add_f32 v[138:139], v[112:113], v[184:185]
	v_cvt_pk_bf16_f32 v112, v116, v117
	v_cvt_pk_bf16_f32 v113, v118, v119
	s_nop 0
	v_cvt_pk_bf16_f32 v114, v138, v139
	v_cvt_pk_bf16_f32 v115, v136, v137
	global_store_dwordx4 v[238:239], v[112:115], off offset:256
	s_nop 1
	v_mul_f32_e32 v114, v145, v145
	v_mul_f32_e32 v115, v147, v147
	v_fmac_f32_e32 v114, v144, v144
	v_fmac_f32_e32 v115, v146, v146
	v_mul_f32_e32 v113, v191, v191
	v_add_f32_e32 v114, v114, v115
	v_mul_f32_e32 v115, v117, v117
	v_mul_f32_e32 v112, v189, v189
	v_fmac_f32_e32 v113, v190, v190
	v_fmac_f32_e32 v115, v116, v116
	v_mul_f32_e32 v116, v119, v119
	v_fmac_f32_e32 v112, v188, v188
	v_add_f32_e32 v113, v113, v114
	v_mul_f32_e32 v114, v139, v139
	v_fmac_f32_e32 v116, v118, v118
	v_add_f32_e32 v112, v112, v113
	v_mul_f32_e32 v113, v137, v137
	v_fmac_f32_e32 v114, v138, v138
	v_add_f32_e32 v115, v115, v116
	v_fmac_f32_e32 v113, v136, v136
	v_add_f32_e32 v114, v114, v115
	v_add_f32_e32 v113, v113, v114
	v_add_f32_e32 v112, v112, v113
	v_mov_b32_e32 v113, v112
	s_nop 1
	v_permlane16_swap_b32_e32 v112, v113
	v_add_f32_e32 v112, v112, v113
	v_mov_b32_e32 v113, v112
	s_nop 1
	v_permlane32_swap_b32_e32 v112, v113
	s_and_saveexec_b64 s[20:21], vcc
	s_cbranch_execz .LBB0_642
	v_lshl_add_u64 v[114:115], v[236:237], 2, s[10:11]
	v_add_f32_e32 v112, v112, v113
	global_atomic_add_f32 v[114:115], v112, off

.LBB0_955:
	s_lshl_b32 s23, s46, 1
	s_lshr_b32 s25, 64, s23
	s_and_b32 s24, s2, 0xff
	s_add_i32 s25, s25, -1
	s_and_b32 s26, s25, s24
	s_sub_i32 s25, 6, s23
	s_lshr_b32 s24, s24, s25
	s_lshr_b32 s27, s24, 1
	s_lshl_b32 s28, -1, s23
	s_andn2_b32 s27, s27, s28
	s_or_b32 s28, s23, 1
	s_and_b32 s25, s24, 1
	s_lshr_b32 s24, s24, s28
	s_lshl_b32 s24, s24, 14
	s_lshl_b32 s28, s46, 9
	s_or_b32 s88, s24, s27
	s_lshl_b32 s24, s25, 2
	s_ashr_i32 s29, s28, 31
	s_xor_b64 s[86:87], s[84:85], -1
	s_add_i32 s24, s24, s10
	s_lshl_b64 s[28:29], s[28:29], 1
	s_add_u32 s27, s4, s28
	s_addc_u32 s29, s5, s29
	s_lshl_b32 s25, s25, 8
	s_add_u32 s28, s27, s25
	s_addc_u32 s29, s29, 0
	s_ashr_i32 s47, s46, 31
	s_lshl_b64 s[42:43], s[46:47], 2
	s_add_u32 s42, s62, s42
	s_addc_u32 s43, s63, s43
	global_load_dword v84, v239, s[42:43] offset:3072
	s_lshl_b32 s42, s46, 10
	s_ashr_i32 s43, s42, 31
	s_lshl_b64 s[42:43], s[42:43], 1
	s_add_u32 s25, s8, s42
	s_addc_u32 s27, s9, s43
	s_lshl_b32 s42, s24, 8
	s_add_u32 s90, s25, s42
	s_addc_u32 s91, s27, 0
	s_lshl_b32 s27, s26, 8
	v_or_b32_e32 v156, s27, v219
	v_lshlrev_b64 v[52:53], s23, v[156:157]
	v_or_b32_e32 v156, 16, v156
	s_mov_b32 s89, s65
	v_lshlrev_b64 v[66:67], s23, v[156:157]
	v_lshl_add_u64 v[168:169], v[158:159], 1, s[90:91]
	v_lshl_add_u64 v[52:53], v[52:53], 0, s[88:89]
	v_lshl_add_u64 v[66:67], v[66:67], 0, s[88:89]
	v_mad_u64_u32 v[64:65], s[42:43], v52, s20, v[168:169]
	v_mad_u64_u32 v[80:81], s[42:43], v66, s20, v[168:169]
	v_mov_b32_e32 v52, v65
	v_mov_b32_e32 v66, v81
	v_mad_u64_u32 v[52:53], s[42:43], v53, s20, v[52:53]
	v_mad_u64_u32 v[66:67], s[42:43], v67, s20, v[66:67]
	v_mov_b32_e32 v65, v52
	v_mov_b32_e32 v81, v66
	global_load_dwordx4 v[52:55], v[64:65], off offset:64 nt
	global_load_dwordx4 v[56:59], v[64:65], off offset:128 nt
	global_load_dwordx4 v[60:63], v[64:65], off offset:192 nt
	global_load_dwordx4 v[68:71], v[80:81], off nt
	global_load_dwordx4 v[72:75], v[80:81], off offset:64 nt
	global_load_dwordx4 v[76:79], v[80:81], off offset:128 nt
	s_nop 0
	global_load_dwordx4 v[64:67], v[64:65], off nt
	s_nop 0
	global_load_dwordx4 v[80:83], v[80:81], off offset:192 nt
	v_mov_b32_e32 v165, v157
	s_cmp_lg_u32 s26, 0
	v_lshl_add_u64 v[170:171], s[28:29], 0, v[164:165]
	s_cselect_b64 s[48:49], -1, 0
	s_cmp_eq_u32 s26, 0
	s_waitcnt vmcnt(8)
	v_readfirstlane_b32 s25, v84
	v_add_u32_e32 v84, 0xffffff80, v218
	v_add_u32_e32 v94, s27, v84
	s_cbranch_scc1 .LBB0_957
	v_ashrrev_i32_e32 v95, 31, v94
	v_lshlrev_b64 v[84:85], s23, v[94:95]
	v_lshl_add_u64 v[84:85], v[84:85], 0, s[88:89]
	v_mad_u64_u32 v[86:87], s[28:29], v84, s21, v[170:171]
	v_mov_b32_e32 v84, v87
	v_mad_u64_u32 v[84:85], s[28:29], v85, s21, v[84:85]
	v_mov_b32_e32 v87, v84
	global_load_dwordx4 v[88:91], v[86:87], off
	s_nop 0
	global_load_dwordx4 v[84:87], v[86:87], off offset:512
	s_branch .LBB0_958

.LBB0_967:
	s_cmp_lg_u32 s27, 0x1a400
	s_cselect_b64 s[46:47], -1, 0
	s_cmp_eq_u32 s27, 0x1a400
	v_lshl_add_u64 v[182:183], v[172:173], 0, s[92:93]
	s_cbranch_scc1 .LBB0_969
	v_lshl_add_u64 v[4:5], v[180:181], 0, s[92:93]
	v_lshl_add_u64 v[12:13], v[174:175], 0, s[92:93]
	v_lshl_add_u64 v[20:21], v[182:183], 0, 64
	v_lshl_add_u64 v[36:37], v[156:157], 0, s[92:93]
	v_lshlrev_b64 v[4:5], s23, v[4:5]
	v_lshlrev_b64 v[12:13], s23, v[12:13]
	v_lshlrev_b64 v[20:21], s23, v[20:21]
	v_lshlrev_b64 v[36:37], s23, v[36:37]
	v_lshl_add_u64 v[4:5], v[4:5], 0, s[88:89]
	v_lshl_add_u64 v[12:13], v[12:13], 0, s[88:89]
	v_lshl_add_u64 v[20:21], v[20:21], 0, s[88:89]
	v_lshl_add_u64 v[36:37], v[36:37], 0, s[88:89]
	v_mad_u64_u32 v[8:9], s[42:43], v4, s21, v[170:171]
	v_mad_u64_u32 v[16:17], s[42:43], v12, s21, v[170:171]
	v_mad_u64_u32 v[22:23], s[42:43], v20, s20, v[168:169]
	v_mad_u64_u32 v[38:39], s[42:43], v36, s20, v[168:169]
	v_mov_b32_e32 v4, v9
	v_mov_b32_e32 v12, v17
	v_mov_b32_e32 v20, v23
	v_mov_b32_e32 v36, v39
	v_mad_u64_u32 v[4:5], s[42:43], v5, s21, v[4:5]
	v_mad_u64_u32 v[12:13], s[42:43], v13, s21, v[12:13]
	v_mad_u64_u32 v[20:21], s[42:43], v21, s20, v[20:21]
	v_mad_u64_u32 v[36:37], s[42:43], v37, s20, v[36:37]
	v_mov_b32_e32 v9, v4
	v_mov_b32_e32 v17, v12
	v_mov_b32_e32 v23, v20
	v_mov_b32_e32 v39, v36
	global_load_dwordx4 v[4:7], v[8:9], off
	s_nop 0
	global_load_dwordx4 v[8:11], v[8:9], off offset:512
	s_nop 0
	global_load_dwordx4 v[12:15], v[16:17], off
	s_nop 0
	global_load_dwordx4 v[16:19], v[16:17], off offset:512
	s_nop 0
	global_load_dwordx4 v[32:35], v[22:23], off nt
	global_load_dwordx4 v[28:31], v[22:23], off offset:64 nt
	global_load_dwordx4 v[24:27], v[22:23], off offset:128 nt
	s_nop 0
	global_load_dwordx4 v[20:23], v[22:23], off offset:192 nt
	s_nop 0
	global_load_dwordx4 v[48:51], v[38:39], off nt
	global_load_dwordx4 v[44:47], v[38:39], off offset:64 nt
	global_load_dwordx4 v[40:43], v[38:39], off offset:128 nt
	s_nop 0
	global_load_dwordx4 v[36:39], v[38:39], off offset:192 nt

.LBB0_976:
	s_add_u32 s60, s96, s28
	s_addc_u32 s61, s97, 0
	v_lshl_add_u64 v[152:153], v[160:161], 1, s[60:61]
	s_mov_b64 s[60:61], 0xe000000
	v_lshl_add_u64 v[154:155], v[152:153], 0, s[60:61]
	s_mov_b64 s[60:61], 0x1a000000
	v_lshl_add_u64 v[206:207], v[150:151], 0, s[88:89]
	v_lshl_add_u64 v[152:153], v[152:153], 0, s[60:61]
	v_mad_u64_u32 v[184:185], s[60:61], v206, s20, v[154:155]
	v_mov_b32_e32 v182, v185
	v_lshlrev_b64 v[208:209], 6, v[206:207]
	v_mad_u64_u32 v[182:183], s[60:61], v207, s20, v[182:183]
	v_lshl_add_u64 v[208:209], s[46:47], 0, v[208:209]
	s_lshl_b32 s64, s24, 2
	v_mov_b32_e32 v185, v182
	v_lshl_add_u64 v[208:209], v[208:209], 0, s[64:65]
	global_load_dwordx2 v[214:215], v[184:185], off nt
	global_load_dwordx2 v[216:217], v[184:185], off offset:2048 nt
	global_load_dwordx2 v[210:211], v[184:185], off offset:32 nt
	global_load_dwordx2 v[212:213], v[184:185], off offset:2080 nt
	global_load_dwordx2 v[202:203], v[184:185], off offset:64 nt
	global_load_dwordx2 v[204:205], v[184:185], off offset:2112 nt
	global_load_dwordx2 v[198:199], v[184:185], off offset:96 nt
	global_load_dwordx2 v[200:201], v[184:185], off offset:2144 nt
	global_load_dwordx2 v[194:195], v[184:185], off offset:128 nt
	global_load_dwordx2 v[196:197], v[184:185], off offset:2176 nt
	global_load_dwordx2 v[190:191], v[184:185], off offset:160 nt
	global_load_dwordx2 v[192:193], v[184:185], off offset:2208 nt
	global_load_dwordx2 v[186:187], v[184:185], off offset:192 nt
	global_load_dwordx2 v[188:189], v[184:185], off offset:2240 nt
	global_load_dwordx2 v[182:183], v[184:185], off offset:224 nt
	s_nop 0
	global_load_dwordx2 v[184:185], v[184:185], off offset:2272 nt
	s_nop 0
	global_load_dword v236, v[208:209], off nt
	s_nop 0
	global_load_dword v208, v[208:209], off offset:32 nt
	v_div_scale_f32 v209, s[60:61], v246, v246, 1.0
	v_rcp_f32_e32 v237, v209
	v_lshlrev_b64 v[206:207], 11, v[206:207]
	v_lshl_add_u64 v[206:207], v[152:153], 0, v[206:207]
	v_fma_f32 v247, -v209, v237, 1.0
	v_fmac_f32_e32 v237, v247, v237
	v_div_scale_f32 v247, vcc, 1.0, v246, 1.0
	v_mul_f32_e32 v248, v247, v237
	v_fma_f32 v249, -v209, v248, v247
	v_fmac_f32_e32 v248, v249, v237
	v_fma_f32 v209, -v209, v248, v247
	v_div_fmas_f32 v209, v209, v237, v248
	v_div_fixup_f32 v237, v209, v246, 1.0
	v_log_f32_e32 v209, v246
	s_waitcnt vmcnt(0) lgkmcnt(0)
	v_and_b32_e32 v253, 0xffff0000, v214
	v_add_f32_e32 v247, s25, v209
	v_mul_f32_e32 v209, 0x3f317218, v247
	v_max3_f32 v248, v209, v236, v208
	v_sub_f32_e32 v208, v208, v248
	v_sub_f32_e32 v209, v236, v248
	v_mul_f32_e32 v208, 0x3fb8aa3b, v208
	v_mul_f32_e32 v209, 0x3fb8aa3b, v209
	v_exp_f32_e32 v236, v208
	v_fma_f32 v208, v247, s22, -v248
	v_exp_f32_e32 v209, v209
	v_mul_f32_e32 v208, 0x3fb8aa3b, v208
	v_exp_f32_e32 v208, v208
	v_add_f32_e32 v247, v209, v236
	v_add_f32_e32 v247, v208, v247
	v_div_scale_f32 v248, s[60:61], v247, v247, 1.0
	v_rcp_f32_e32 v249, v248
	s_nop 0
	v_fma_f32 v250, -v248, v249, 1.0
	v_fmac_f32_e32 v249, v250, v249
	v_div_scale_f32 v250, vcc, 1.0, v247, 1.0
	v_mul_f32_e32 v251, v250, v249
	v_fma_f32 v252, -v248, v251, v250
	v_fmac_f32_e32 v251, v252, v249
	v_fma_f32 v248, -v248, v251, v250
	v_div_fmas_f32 v248, v248, v249, v251
	v_div_fixup_f32 v249, v248, v247, 1.0
	v_mul_f32_e32 v248, v237, v249
	v_lshlrev_b32_e32 v251, 16, v214
	v_pk_mul_f32 v[208:209], v[208:209], v[248:249]
	v_mov_b32_e32 v250, v120
	v_mul_f32_e32 v247, v236, v249
	v_lshlrev_b32_e32 v236, 16, v216
	v_pk_mul_f32 v[248:249], v[208:209], v[250:251]
	v_mov_b32_e32 v252, v121
	v_fma_f32 v236, v247, v236, v249
	v_and_b32_e32 v214, 0xffff0000, v216
	v_add_f32_e32 v236, v248, v236
	v_pk_mul_f32 v[248:249], v[208:209], v[252:253]
	v_lshlrev_b32_e32 v237, 16, v215
	v_fma_f32 v214, v247, v214, v249
	v_add_f32_e32 v214, v248, v214
	v_cvt_pk_bf16_f32 v214, v236, v214
	v_mov_b32_e32 v236, v122
	v_lshlrev_b32_e32 v216, 16, v217
	v_pk_mul_f32 v[236:237], v[236:237], v[208:209]
	s_nop 0
	v_fma_f32 v216, v247, v216, v237
	v_add_f32_e32 v248, v236, v216
	v_and_b32_e32 v237, 0xffff0000, v215
	v_mov_b32_e32 v236, v123
	v_and_b32_e32 v215, 0xffff0000, v217
	v_pk_mul_f32 v[216:217], v[208:209], v[236:237]
	s_nop 0
	v_fma_f32 v215, v247, v215, v217
	v_add_f32_e32 v215, v216, v215
	v_cvt_pk_bf16_f32 v215, v248, v215
	global_store_dwordx2 v[206:207], v[214:215], off
	v_lshlrev_b32_e32 v215, 16, v210
	v_mov_b32_e32 v214, v116
	v_lshlrev_b32_e32 v216, 16, v212
	v_pk_mul_f32 v[214:215], v[208:209], v[214:215]
	s_nop 0
	v_fma_f32 v215, v247, v216, v215
	v_add_f32_e32 v216, v214, v215
	v_and_b32_e32 v215, 0xffff0000, v210
	v_mov_b32_e32 v214, v117
	v_and_b32_e32 v210, 0xffff0000, v212
	v_pk_mul_f32 v[214:215], v[208:209], v[214:215]
	v_lshlrev_b32_e32 v212, 16, v213
	v_fma_f32 v210, v247, v210, v215
	v_add_f32_e32 v210, v214, v210
	v_lshlrev_b32_e32 v215, 16, v211
	v_mov_b32_e32 v214, v118
	v_pk_mul_f32 v[214:215], v[208:209], v[214:215]
	v_cvt_pk_bf16_f32 v210, v216, v210
	s_nop 0
	v_fma_f32 v212, v247, v212, v215
	v_add_f32_e32 v216, v214, v212
	v_and_b32_e32 v215, 0xffff0000, v211
	v_mov_b32_e32 v214, v119
	v_and_b32_e32 v211, 0xffff0000, v213
	v_pk_mul_f32 v[212:213], v[208:209], v[214:215]
	s_nop 0
	v_fma_f32 v211, v247, v211, v213
	v_add_f32_e32 v211, v212, v211
	v_cvt_pk_bf16_f32 v211, v216, v211
	global_store_dwordx2 v[206:207], v[210:211], off offset:32
	v_lshlrev_b32_e32 v211, 16, v202
	v_mov_b32_e32 v210, v124
	v_lshlrev_b32_e32 v212, 16, v204
	v_pk_mul_f32 v[210:211], v[208:209], v[210:211]
	s_nop 0
	v_fma_f32 v211, v247, v212, v211
	v_add_f32_e32 v212, v210, v211
	v_and_b32_e32 v211, 0xffff0000, v202
	v_mov_b32_e32 v210, v125
	v_and_b32_e32 v202, 0xffff0000, v204
	v_pk_mul_f32 v[210:211], v[208:209], v[210:211]
	v_lshlrev_b32_e32 v204, 16, v205
	v_fma_f32 v202, v247, v202, v211
	v_add_f32_e32 v202, v210, v202
	v_lshlrev_b32_e32 v211, 16, v203
	v_mov_b32_e32 v210, v126
	v_pk_mul_f32 v[210:211], v[208:209], v[210:211]
	v_cvt_pk_bf16_f32 v202, v212, v202
	s_nop 0
	v_fma_f32 v204, v247, v204, v211
	v_add_f32_e32 v212, v210, v204
	v_and_b32_e32 v211, 0xffff0000, v203
	v_mov_b32_e32 v210, v127
	v_and_b32_e32 v203, 0xffff0000, v205
	v_pk_mul_f32 v[204:205], v[208:209], v[210:211]
	s_nop 0
	v_fma_f32 v203, v247, v203, v205
	v_add_f32_e32 v203, v204, v203
	v_cvt_pk_bf16_f32 v203, v212, v203
	global_store_dwordx2 v[206:207], v[202:203], off offset:64
	v_lshlrev_b32_e32 v203, 16, v198
	v_mov_b32_e32 v202, v132
	v_lshlrev_b32_e32 v204, 16, v200
	v_pk_mul_f32 v[202:203], v[208:209], v[202:203]
	s_nop 0
	v_fma_f32 v203, v247, v204, v203
	v_add_f32_e32 v204, v202, v203
	v_and_b32_e32 v203, 0xffff0000, v198
	v_mov_b32_e32 v202, v133
	v_and_b32_e32 v198, 0xffff0000, v200
	v_pk_mul_f32 v[202:203], v[208:209], v[202:203]
	v_lshlrev_b32_e32 v200, 16, v201
	v_fma_f32 v198, v247, v198, v203
	v_add_f32_e32 v198, v202, v198
	v_lshlrev_b32_e32 v203, 16, v199
	v_mov_b32_e32 v202, v134
	v_pk_mul_f32 v[202:203], v[208:209], v[202:203]
	v_cvt_pk_bf16_f32 v198, v204, v198
	s_nop 0
	v_fma_f32 v200, v247, v200, v203
	v_add_f32_e32 v204, v202, v200
	v_and_b32_e32 v203, 0xffff0000, v199
	v_mov_b32_e32 v202, v135
	v_and_b32_e32 v199, 0xffff0000, v201
	v_pk_mul_f32 v[200:201], v[208:209], v[202:203]
	s_nop 0
	v_fma_f32 v199, v247, v199, v201
	v_add_f32_e32 v199, v200, v199
	v_cvt_pk_bf16_f32 v199, v204, v199
	global_store_dwordx2 v[206:207], v[198:199], off offset:96
	v_lshlrev_b32_e32 v199, 16, v194
	v_mov_b32_e32 v198, v128
	v_lshlrev_b32_e32 v200, 16, v196
	v_pk_mul_f32 v[198:199], v[208:209], v[198:199]
	s_nop 0
	v_fma_f32 v199, v247, v200, v199
	v_add_f32_e32 v200, v198, v199
	v_and_b32_e32 v199, 0xffff0000, v194
	v_mov_b32_e32 v198, v129
	v_and_b32_e32 v194, 0xffff0000, v196
	v_pk_mul_f32 v[198:199], v[208:209], v[198:199]
	v_lshlrev_b32_e32 v196, 16, v197
	v_fma_f32 v194, v247, v194, v199
	v_add_f32_e32 v194, v198, v194
	v_lshlrev_b32_e32 v199, 16, v195
	v_mov_b32_e32 v198, v130
	v_pk_mul_f32 v[198:199], v[208:209], v[198:199]
	v_cvt_pk_bf16_f32 v194, v200, v194
	s_nop 0
	v_fma_f32 v196, v247, v196, v199
	v_add_f32_e32 v200, v198, v196
	v_and_b32_e32 v199, 0xffff0000, v195
	v_mov_b32_e32 v198, v131
	v_and_b32_e32 v195, 0xffff0000, v197
	v_pk_mul_f32 v[196:197], v[208:209], v[198:199]
	s_nop 0
	v_fma_f32 v195, v247, v195, v197
	v_add_f32_e32 v195, v196, v195
	v_cvt_pk_bf16_f32 v195, v200, v195
	global_store_dwordx2 v[206:207], v[194:195], off offset:128
	v_lshlrev_b32_e32 v195, 16, v190
	v_mov_b32_e32 v194, v136
	v_lshlrev_b32_e32 v196, 16, v192
	v_pk_mul_f32 v[194:195], v[208:209], v[194:195]
	s_nop 0
	v_fma_f32 v195, v247, v196, v195
	v_add_f32_e32 v196, v194, v195
	v_and_b32_e32 v195, 0xffff0000, v190
	v_mov_b32_e32 v194, v137
	v_and_b32_e32 v190, 0xffff0000, v192
	v_pk_mul_f32 v[194:195], v[208:209], v[194:195]
	v_lshlrev_b32_e32 v192, 16, v193
	v_fma_f32 v190, v247, v190, v195
	v_add_f32_e32 v190, v194, v190
	v_lshlrev_b32_e32 v195, 16, v191
	v_mov_b32_e32 v194, v138
	v_pk_mul_f32 v[194:195], v[208:209], v[194:195]
	v_cvt_pk_bf16_f32 v190, v196, v190
	s_nop 0
	v_fma_f32 v192, v247, v192, v195
	v_add_f32_e32 v196, v194, v192
	v_and_b32_e32 v195, 0xffff0000, v191
	v_mov_b32_e32 v194, v139
	v_and_b32_e32 v191, 0xffff0000, v193
	v_pk_mul_f32 v[192:193], v[208:209], v[194:195]
	s_nop 0
	v_fma_f32 v191, v247, v191, v193
	v_add_f32_e32 v191, v192, v191
	v_cvt_pk_bf16_f32 v191, v196, v191
	global_store_dwordx2 v[206:207], v[190:191], off offset:160
	v_lshlrev_b32_e32 v191, 16, v186
	v_mov_b32_e32 v190, v140
	v_lshlrev_b32_e32 v192, 16, v188
	v_pk_mul_f32 v[190:191], v[208:209], v[190:191]
	s_nop 0
	v_fma_f32 v191, v247, v192, v191
	v_add_f32_e32 v192, v190, v191
	v_and_b32_e32 v191, 0xffff0000, v186
	v_mov_b32_e32 v190, v141
	v_and_b32_e32 v186, 0xffff0000, v188
	v_pk_mul_f32 v[190:191], v[208:209], v[190:191]
	v_lshlrev_b32_e32 v188, 16, v189
	v_fma_f32 v186, v247, v186, v191
	v_add_f32_e32 v186, v190, v186
	v_lshlrev_b32_e32 v191, 16, v187
	v_mov_b32_e32 v190, v142
	v_pk_mul_f32 v[190:191], v[208:209], v[190:191]
	v_cvt_pk_bf16_f32 v186, v192, v186
	s_nop 0
	v_fma_f32 v188, v247, v188, v191
	v_add_f32_e32 v192, v190, v188
	v_and_b32_e32 v191, 0xffff0000, v187
	v_mov_b32_e32 v190, v143
	v_and_b32_e32 v187, 0xffff0000, v189
	v_pk_mul_f32 v[188:189], v[208:209], v[190:191]
	s_nop 0
	v_fma_f32 v187, v247, v187, v189
	v_add_f32_e32 v187, v188, v187
	v_cvt_pk_bf16_f32 v187, v192, v187
	global_store_dwordx2 v[206:207], v[186:187], off offset:192
	v_lshlrev_b32_e32 v187, 16, v182
	v_mov_b32_e32 v186, v144
	v_lshlrev_b32_e32 v188, 16, v184
	v_pk_mul_f32 v[186:187], v[208:209], v[186:187]
	s_nop 0
	v_fma_f32 v187, v247, v188, v187
	v_add_f32_e32 v188, v186, v187
	v_and_b32_e32 v187, 0xffff0000, v182
	v_mov_b32_e32 v186, v145
	v_and_b32_e32 v182, 0xffff0000, v184
	v_pk_mul_f32 v[186:187], v[208:209], v[186:187]
	v_lshlrev_b32_e32 v184, 16, v185
	v_fma_f32 v182, v247, v182, v187
	v_add_f32_e32 v182, v186, v182
	v_lshlrev_b32_e32 v187, 16, v183
	v_mov_b32_e32 v186, v146
	v_pk_mul_f32 v[186:187], v[208:209], v[186:187]
	v_cvt_pk_bf16_f32 v182, v188, v182
	s_nop 0
	v_fma_f32 v184, v247, v184, v187
	v_add_f32_e32 v188, v186, v184
	v_and_b32_e32 v187, 0xffff0000, v183
	v_mov_b32_e32 v186, v147
	v_and_b32_e32 v183, 0xffff0000, v185
	v_pk_mul_f32 v[184:185], v[208:209], v[186:187]
	s_nop 0
	v_fma_f32 v183, v247, v183, v185
	v_add_f32_e32 v183, v184, v183
	v_cvt_pk_bf16_f32 v183, v188, v183
	global_store_dwordx2 v[206:207], v[182:183], off offset:224
	v_lshlrev_b64 v[182:183], s23, v[148:149]
	v_lshl_add_u64 v[212:213], v[182:183], 0, s[88:89]
	v_mad_u64_u32 v[182:183], s[60:61], v212, s20, v[154:155]
	v_mov_b32_e32 v154, v183
	v_lshlrev_b64 v[214:215], 6, v[212:213]
	v_mad_u64_u32 v[154:155], s[60:61], v213, s20, v[154:155]
	v_lshl_add_u64 v[214:215], s[46:47], 0, v[214:215]
	v_mov_b32_e32 v183, v154
	v_lshl_add_u64 v[214:215], v[214:215], 0, s[64:65]
	global_load_dwordx2 v[208:209], v[182:183], off nt
	global_load_dwordx2 v[210:211], v[182:183], off offset:2048 nt
	global_load_dwordx2 v[204:205], v[182:183], off offset:32 nt
	global_load_dwordx2 v[206:207], v[182:183], off offset:2080 nt
	global_load_dwordx2 v[200:201], v[182:183], off offset:64 nt
	global_load_dwordx2 v[202:203], v[182:183], off offset:2112 nt
	global_load_dwordx2 v[196:197], v[182:183], off offset:96 nt
	global_load_dwordx2 v[198:199], v[182:183], off offset:2144 nt
	global_load_dwordx2 v[192:193], v[182:183], off offset:128 nt
	global_load_dwordx2 v[194:195], v[182:183], off offset:2176 nt
	global_load_dwordx2 v[188:189], v[182:183], off offset:160 nt
	global_load_dwordx2 v[190:191], v[182:183], off offset:2208 nt
	global_load_dwordx2 v[184:185], v[182:183], off offset:192 nt
	global_load_dwordx2 v[186:187], v[182:183], off offset:2240 nt
	global_load_dwordx2 v[154:155], v[182:183], off offset:224 nt
	s_nop 0
	global_load_dwordx2 v[182:183], v[182:183], off offset:2272 nt
	s_nop 0
	global_load_dword v216, v[214:215], off nt
	s_nop 0
	global_load_dword v214, v[214:215], off offset:32 nt
	v_div_scale_f32 v215, s[60:61], v167, v167, 1.0
	v_rcp_f32_e32 v217, v215
	v_lshlrev_b64 v[212:213], 11, v[212:213]
	v_lshl_add_u64 v[152:153], v[152:153], 0, v[212:213]
	v_fma_f32 v236, -v215, v217, 1.0
	v_fmac_f32_e32 v217, v236, v217
	v_div_scale_f32 v236, vcc, 1.0, v167, 1.0
	v_mul_f32_e32 v237, v236, v217
	v_fma_f32 v247, -v215, v237, v236
	v_fmac_f32_e32 v237, v247, v217
	v_fma_f32 v215, -v215, v237, v236
	v_div_fmas_f32 v215, v215, v217, v237
	v_div_fixup_f32 v236, v215, v167, 1.0
	v_log_f32_e32 v215, v167
	s_waitcnt vmcnt(0) lgkmcnt(0)
	v_lshlrev_b32_e32 v251, 16, v209
	v_add_f32_e32 v217, s25, v215
	v_mul_f32_e32 v215, 0x3f317218, v217
	v_max3_f32 v237, v215, v216, v214
	v_sub_f32_e32 v214, v214, v237
	v_sub_f32_e32 v215, v216, v237
	v_mul_f32_e32 v214, 0x3fb8aa3b, v214
	v_mul_f32_e32 v215, 0x3fb8aa3b, v215
	v_exp_f32_e32 v216, v214
	v_fma_f32 v214, v217, s22, -v237
	v_exp_f32_e32 v215, v215
	v_mul_f32_e32 v214, 0x3fb8aa3b, v214
	v_exp_f32_e32 v214, v214
	v_add_f32_e32 v217, v215, v216
	v_add_f32_e32 v217, v214, v217
	v_div_scale_f32 v237, s[60:61], v217, v217, 1.0
	v_rcp_f32_e32 v247, v237
	s_nop 0
	v_fma_f32 v248, -v237, v247, 1.0
	v_fmac_f32_e32 v247, v248, v247
	v_div_scale_f32 v248, vcc, 1.0, v217, 1.0
	v_mul_f32_e32 v249, v248, v247
	v_fma_f32 v250, -v237, v249, v248
	v_fmac_f32_e32 v249, v250, v247
	v_fma_f32 v237, -v237, v249, v248
	v_div_fmas_f32 v237, v237, v247, v249
	v_div_fixup_f32 v217, v237, v217, 1.0
	v_mul_f32_e32 v247, v216, v217
	v_mul_f32_e32 v216, v236, v217
	v_lshlrev_b32_e32 v237, 16, v208
	v_pk_mul_f32 v[212:213], v[214:215], v[216:217]
	v_mov_b32_e32 v236, v88
	v_lshlrev_b32_e32 v248, 16, v210
	v_pk_mul_f32 v[214:215], v[212:213], v[236:237]
	v_and_b32_e32 v249, 0xffff0000, v208
	v_fma_f32 v215, v247, v248, v215
	v_mov_b32_e32 v248, v89
	v_and_b32_e32 v208, 0xffff0000, v210
	v_add_f32_e32 v216, v214, v215
	v_pk_mul_f32 v[214:215], v[212:213], v[248:249]
	v_mov_b32_e32 v250, v90
	v_fma_f32 v208, v247, v208, v215
	v_lshlrev_b32_e32 v210, 16, v211
	v_add_f32_e32 v208, v214, v208
	v_pk_mul_f32 v[214:215], v[250:251], v[212:213]
	v_cvt_pk_bf16_f32 v208, v216, v208
	s_nop 0
	v_fma_f32 v210, v247, v210, v215
	v_add_f32_e32 v216, v214, v210
	v_and_b32_e32 v215, 0xffff0000, v209
	v_mov_b32_e32 v214, v91
	v_and_b32_e32 v209, 0xffff0000, v211
	v_pk_mul_f32 v[210:211], v[212:213], v[214:215]
	s_nop 0
	v_fma_f32 v209, v247, v209, v211
	v_add_f32_e32 v209, v210, v209
	v_cvt_pk_bf16_f32 v209, v216, v209
	global_store_dwordx2 v[152:153], v[208:209], off
	v_lshlrev_b32_e32 v209, 16, v204
	v_mov_b32_e32 v208, v84
	v_lshlrev_b32_e32 v210, 16, v206
	v_pk_mul_f32 v[208:209], v[212:213], v[208:209]
	s_nop 0
	v_fma_f32 v209, v247, v210, v209
	v_add_f32_e32 v210, v208, v209
	v_and_b32_e32 v209, 0xffff0000, v204
	v_mov_b32_e32 v208, v85
	v_and_b32_e32 v204, 0xffff0000, v206
	v_pk_mul_f32 v[208:209], v[212:213], v[208:209]
	v_lshlrev_b32_e32 v206, 16, v207
	v_fma_f32 v204, v247, v204, v209
	v_add_f32_e32 v204, v208, v204
	v_lshlrev_b32_e32 v209, 16, v205
	v_mov_b32_e32 v208, v86
	v_pk_mul_f32 v[208:209], v[212:213], v[208:209]
	v_cvt_pk_bf16_f32 v204, v210, v204
	s_nop 0
	v_fma_f32 v206, v247, v206, v209
	v_add_f32_e32 v210, v208, v206
	v_and_b32_e32 v209, 0xffff0000, v205
	v_mov_b32_e32 v208, v87
	v_and_b32_e32 v205, 0xffff0000, v207
	v_pk_mul_f32 v[206:207], v[212:213], v[208:209]
	s_nop 0
	v_fma_f32 v205, v247, v205, v207
	v_add_f32_e32 v205, v206, v205
	v_cvt_pk_bf16_f32 v205, v210, v205
	global_store_dwordx2 v[152:153], v[204:205], off offset:32
	v_lshlrev_b32_e32 v205, 16, v200
	v_mov_b32_e32 v204, v92
	v_lshlrev_b32_e32 v206, 16, v202
	v_pk_mul_f32 v[204:205], v[212:213], v[204:205]
	s_nop 0
	v_fma_f32 v205, v247, v206, v205
	v_add_f32_e32 v206, v204, v205
	v_and_b32_e32 v205, 0xffff0000, v200
	v_mov_b32_e32 v204, v93
	v_and_b32_e32 v200, 0xffff0000, v202
	v_pk_mul_f32 v[204:205], v[212:213], v[204:205]
	v_lshlrev_b32_e32 v202, 16, v203
	v_fma_f32 v200, v247, v200, v205
	v_add_f32_e32 v200, v204, v200
	v_lshlrev_b32_e32 v205, 16, v201
	v_mov_b32_e32 v204, v94
	v_pk_mul_f32 v[204:205], v[212:213], v[204:205]
	v_cvt_pk_bf16_f32 v200, v206, v200
	s_nop 0
	v_fma_f32 v202, v247, v202, v205
	v_add_f32_e32 v206, v204, v202
	v_and_b32_e32 v205, 0xffff0000, v201
	v_mov_b32_e32 v204, v95
	v_and_b32_e32 v201, 0xffff0000, v203
	v_pk_mul_f32 v[202:203], v[212:213], v[204:205]
	s_nop 0
	v_fma_f32 v201, v247, v201, v203
	v_add_f32_e32 v201, v202, v201
	v_cvt_pk_bf16_f32 v201, v206, v201
	global_store_dwordx2 v[152:153], v[200:201], off offset:64
	v_lshlrev_b32_e32 v201, 16, v196
	v_mov_b32_e32 v200, v100
	v_lshlrev_b32_e32 v202, 16, v198
	v_pk_mul_f32 v[200:201], v[212:213], v[200:201]
	s_nop 0
	v_fma_f32 v201, v247, v202, v201
	v_add_f32_e32 v202, v200, v201
	v_and_b32_e32 v201, 0xffff0000, v196
	v_mov_b32_e32 v200, v101
	v_and_b32_e32 v196, 0xffff0000, v198
	v_pk_mul_f32 v[200:201], v[212:213], v[200:201]
	v_lshlrev_b32_e32 v198, 16, v199
	v_fma_f32 v196, v247, v196, v201
	v_add_f32_e32 v196, v200, v196
	v_lshlrev_b32_e32 v201, 16, v197
	v_mov_b32_e32 v200, v102
	v_pk_mul_f32 v[200:201], v[212:213], v[200:201]
	v_cvt_pk_bf16_f32 v196, v202, v196
	s_nop 0
	v_fma_f32 v198, v247, v198, v201
	v_add_f32_e32 v202, v200, v198
	v_and_b32_e32 v201, 0xffff0000, v197
	v_mov_b32_e32 v200, v103
	v_and_b32_e32 v197, 0xffff0000, v199
	v_pk_mul_f32 v[198:199], v[212:213], v[200:201]
	s_nop 0
	v_fma_f32 v197, v247, v197, v199
	v_add_f32_e32 v197, v198, v197
	v_cvt_pk_bf16_f32 v197, v202, v197
	global_store_dwordx2 v[152:153], v[196:197], off offset:96
	v_lshlrev_b32_e32 v197, 16, v192
	v_mov_b32_e32 v196, v96
	v_lshlrev_b32_e32 v198, 16, v194
	v_pk_mul_f32 v[196:197], v[212:213], v[196:197]
	s_nop 0
	v_fma_f32 v197, v247, v198, v197
	v_add_f32_e32 v198, v196, v197
	v_and_b32_e32 v197, 0xffff0000, v192
	v_mov_b32_e32 v196, v97
	v_and_b32_e32 v192, 0xffff0000, v194
	v_pk_mul_f32 v[196:197], v[212:213], v[196:197]
	v_lshlrev_b32_e32 v194, 16, v195
	v_fma_f32 v192, v247, v192, v197
	v_add_f32_e32 v192, v196, v192
	v_lshlrev_b32_e32 v197, 16, v193
	v_mov_b32_e32 v196, v98
	v_pk_mul_f32 v[196:197], v[212:213], v[196:197]
	v_cvt_pk_bf16_f32 v192, v198, v192
	s_nop 0
	v_fma_f32 v194, v247, v194, v197
	v_add_f32_e32 v198, v196, v194
	v_and_b32_e32 v197, 0xffff0000, v193
	v_mov_b32_e32 v196, v99
	v_and_b32_e32 v193, 0xffff0000, v195
	v_pk_mul_f32 v[194:195], v[212:213], v[196:197]
	s_nop 0
	v_fma_f32 v193, v247, v193, v195
	v_add_f32_e32 v193, v194, v193
	v_cvt_pk_bf16_f32 v193, v198, v193
	global_store_dwordx2 v[152:153], v[192:193], off offset:128
	v_lshlrev_b32_e32 v193, 16, v188
	v_mov_b32_e32 v192, v104
	v_lshlrev_b32_e32 v194, 16, v190
	v_pk_mul_f32 v[192:193], v[212:213], v[192:193]
	s_nop 0
	v_fma_f32 v193, v247, v194, v193
	v_add_f32_e32 v194, v192, v193
	v_and_b32_e32 v193, 0xffff0000, v188
	v_mov_b32_e32 v192, v105
	v_and_b32_e32 v188, 0xffff0000, v190
	v_pk_mul_f32 v[192:193], v[212:213], v[192:193]
	v_lshlrev_b32_e32 v190, 16, v191
	v_fma_f32 v188, v247, v188, v193
	v_add_f32_e32 v188, v192, v188
	v_lshlrev_b32_e32 v193, 16, v189
	v_mov_b32_e32 v192, v106
	v_pk_mul_f32 v[192:193], v[212:213], v[192:193]
	v_cvt_pk_bf16_f32 v188, v194, v188
	s_nop 0
	v_fma_f32 v190, v247, v190, v193
	v_add_f32_e32 v194, v192, v190
	v_and_b32_e32 v193, 0xffff0000, v189
	v_mov_b32_e32 v192, v107
	v_and_b32_e32 v189, 0xffff0000, v191
	v_pk_mul_f32 v[190:191], v[212:213], v[192:193]
	s_nop 0
	v_fma_f32 v189, v247, v189, v191
	v_add_f32_e32 v189, v190, v189
	v_cvt_pk_bf16_f32 v189, v194, v189
	global_store_dwordx2 v[152:153], v[188:189], off offset:160
	v_lshlrev_b32_e32 v189, 16, v184
	v_mov_b32_e32 v188, v108
	v_lshlrev_b32_e32 v190, 16, v186
	v_pk_mul_f32 v[188:189], v[212:213], v[188:189]
	s_nop 0
	v_fma_f32 v189, v247, v190, v189
	v_add_f32_e32 v190, v188, v189
	v_and_b32_e32 v189, 0xffff0000, v184
	v_mov_b32_e32 v188, v109
	v_and_b32_e32 v184, 0xffff0000, v186
	v_pk_mul_f32 v[188:189], v[212:213], v[188:189]
	v_lshlrev_b32_e32 v186, 16, v187
	v_fma_f32 v184, v247, v184, v189
	v_add_f32_e32 v184, v188, v184
	v_lshlrev_b32_e32 v189, 16, v185
	v_mov_b32_e32 v188, v110
	v_pk_mul_f32 v[188:189], v[212:213], v[188:189]
	v_cvt_pk_bf16_f32 v184, v190, v184
	s_nop 0
	v_fma_f32 v186, v247, v186, v189
	v_add_f32_e32 v190, v188, v186
	v_and_b32_e32 v189, 0xffff0000, v185
	v_mov_b32_e32 v188, v111
	v_and_b32_e32 v185, 0xffff0000, v187
	v_pk_mul_f32 v[186:187], v[212:213], v[188:189]
	s_nop 0
	v_fma_f32 v185, v247, v185, v187
	v_add_f32_e32 v185, v186, v185
	v_cvt_pk_bf16_f32 v185, v190, v185
	global_store_dwordx2 v[152:153], v[184:185], off offset:192
	v_lshlrev_b32_e32 v185, 16, v154
	v_mov_b32_e32 v184, v112
	v_lshlrev_b32_e32 v186, 16, v182
	v_pk_mul_f32 v[184:185], v[212:213], v[184:185]
	s_nop 0
	v_fma_f32 v185, v247, v186, v185
	v_add_f32_e32 v186, v184, v185
	v_and_b32_e32 v185, 0xffff0000, v154
	v_mov_b32_e32 v184, v113
	v_and_b32_e32 v154, 0xffff0000, v182
	v_pk_mul_f32 v[184:185], v[212:213], v[184:185]
	v_lshlrev_b32_e32 v182, 16, v183
	v_fma_f32 v154, v247, v154, v185
	v_add_f32_e32 v154, v184, v154
	v_lshlrev_b32_e32 v185, 16, v155
	v_mov_b32_e32 v184, v114
	v_pk_mul_f32 v[184:185], v[212:213], v[184:185]
	v_cvt_pk_bf16_f32 v154, v186, v154
	s_nop 0
	v_fma_f32 v182, v247, v182, v185
	v_add_f32_e32 v186, v184, v182
	v_and_b32_e32 v185, 0xffff0000, v155
	v_mov_b32_e32 v184, v115
	v_and_b32_e32 v155, 0xffff0000, v183
	v_pk_mul_f32 v[182:183], v[212:213], v[184:185]
	s_nop 0
	v_fma_f32 v155, v247, v155, v183
	v_add_f32_e32 v155, v182, v155
	v_cvt_pk_bf16_f32 v155, v186, v155
	global_store_dwordx2 v[152:153], v[154:155], off offset:224
	s_cbranch_execnz .LBB0_975

.LBB0_1112:
	s_lshl_b32 s17, s26, 8
	v_mov_b32_e32 v120, v244
	v_mov_b32_e32 v249, v243
	s_add_i32 s17, s17, s42
	s_nop 0
	v_add_u32_e32 v236, s17, v120
	s_lshl_b32 s17, s24, 8
	s_or_b32 s17, s17, s43
	v_lshl_add_u32 v206, v249, 3, s17
	v_ashrrev_i32_e32 v207, 31, v206
	v_lshlrev_b64 v[238:239], 1, v[206:207]
	v_ashrrev_i32_e32 v237, 31, v236
	v_lshl_add_u64 v[124:125], s[58:59], 0, v[238:239]
	v_lshlrev_b64 v[240:241], 11, v[236:237]
	v_lshl_add_u64 v[120:121], v[124:125], 0, v[240:241]
	global_load_dwordx4 v[188:191], v[120:121], off nt
	global_load_dwordx4 v[184:187], v[120:121], off offset:256 nt
	v_add_u32_e32 v232, 16, v236
	v_ashrrev_i32_e32 v233, 31, v232
	v_add_u32_e32 v228, 32, v236
	v_lshlrev_b64 v[234:235], 11, v[232:233]
	v_ashrrev_i32_e32 v229, 31, v228
	v_add_u32_e32 v224, 48, v236
	v_lshl_add_u64 v[120:121], v[124:125], 0, v[234:235]
	v_lshlrev_b64 v[230:231], 11, v[228:229]
	v_ashrrev_i32_e32 v225, 31, v224
	v_add_u32_e32 v220, 0x80, v236
	global_load_dwordx4 v[180:183], v[120:121], off nt
	global_load_dwordx4 v[176:179], v[120:121], off offset:256 nt
	v_lshl_add_u64 v[120:121], v[124:125], 0, v[230:231]
	v_lshlrev_b64 v[226:227], 11, v[224:225]
	v_ashrrev_i32_e32 v221, 31, v220
	v_add_u32_e32 v216, 0x90, v236
	global_load_dwordx4 v[172:175], v[120:121], off nt
	global_load_dwordx4 v[168:171], v[120:121], off offset:256 nt
	v_lshl_add_u64 v[120:121], v[124:125], 0, v[226:227]
	v_lshlrev_b64 v[222:223], 11, v[220:221]
	v_ashrrev_i32_e32 v217, 31, v216
	v_add_u32_e32 v210, 0xa0, v236
	v_add_u32_e32 v208, 0xb0, v236
	global_load_dwordx4 v[164:167], v[120:121], off nt
	global_load_dwordx4 v[160:163], v[120:121], off offset:256 nt
	v_lshl_add_u64 v[120:121], v[124:125], 0, v[222:223]
	v_lshlrev_b64 v[218:219], 11, v[216:217]
	v_ashrrev_i32_e32 v211, 31, v210
	v_ashrrev_i32_e32 v209, 31, v208
	global_load_dwordx4 v[156:159], v[120:121], off nt
	global_load_dwordx4 v[152:155], v[120:121], off offset:256 nt
	v_lshl_add_u64 v[120:121], v[124:125], 0, v[218:219]
	v_lshlrev_b64 v[214:215], 11, v[210:211]
	v_lshlrev_b64 v[212:213], 11, v[208:209]
	global_load_dwordx4 v[148:151], v[120:121], off nt
	global_load_dwordx4 v[140:143], v[120:121], off offset:256 nt
	v_lshl_add_u64 v[120:121], v[124:125], 0, v[214:215]
	v_lshl_add_u64 v[124:125], v[124:125], 0, v[212:213]
	global_load_dwordx4 v[128:131], v[120:121], off nt
	s_nop 0
	global_load_dwordx4 v[120:123], v[120:121], off offset:256 nt
	s_nop 0
	global_load_dwordx4 v[132:135], v[124:125], off nt
	s_nop 0
	global_load_dwordx4 v[124:127], v[124:125], off offset:256 nt
	v_lshl_add_u64 v[240:241], s[58:59], 0, v[240:241]
	v_lshl_add_u64 v[238:239], v[240:241], 0, v[238:239]
	v_cmp_eq_u32_e32 vcc, 0, v249
	s_waitcnt vmcnt(0)
	v_lshlrev_b32_e32 v250, 16, v188
	v_and_b32_e32 v251, 0xffff0000, v188
	v_lshlrev_b32_e32 v188, 16, v189
	v_and_b32_e32 v189, 0xffff0000, v189
	v_lshlrev_b32_e32 v252, 16, v190
	v_and_b32_e32 v253, 0xffff0000, v190
	v_lshlrev_b32_e32 v190, 16, v191
	v_and_b32_e32 v191, 0xffff0000, v191
	v_pk_add_f32 v[146:147], v[146:147], v[188:189]
	v_pk_add_f32 v[144:145], v[144:145], v[250:251]
	v_pk_add_f32 v[188:189], v[138:139], v[190:191]
	v_pk_add_f32 v[190:191], v[136:137], v[252:253]
	v_cvt_pk_bf16_f32 v136, v144, v145
	v_cvt_pk_bf16_f32 v137, v146, v147
	s_nop 0
	v_cvt_pk_bf16_f32 v138, v190, v191
	v_cvt_pk_bf16_f32 v139, v188, v189
	global_store_dwordx4 v[238:239], v[136:139], off
	s_nop 1
	v_lshlrev_b32_e32 v136, 16, v184
	v_and_b32_e32 v137, 0xffff0000, v184
	v_lshlrev_b32_e32 v138, 16, v185
	v_and_b32_e32 v139, 0xffff0000, v185
	v_lshlrev_b32_e32 v184, 16, v186
	v_and_b32_e32 v185, 0xffff0000, v186
	v_lshlrev_b32_e32 v186, 16, v187
	v_and_b32_e32 v187, 0xffff0000, v187
	v_pk_add_f32 v[118:119], v[118:119], v[138:139]
	v_pk_add_f32 v[116:117], v[116:117], v[136:137]
	v_pk_add_f32 v[136:137], v[114:115], v[186:187]
	v_pk_add_f32 v[138:139], v[112:113], v[184:185]
	v_cvt_pk_bf16_f32 v112, v116, v117
	v_cvt_pk_bf16_f32 v113, v118, v119
	s_nop 0
	v_cvt_pk_bf16_f32 v114, v138, v139
	v_cvt_pk_bf16_f32 v115, v136, v137
	global_store_dwordx4 v[238:239], v[112:115], off offset:256
	s_nop 1
	v_mul_f32_e32 v114, v145, v145
	v_mul_f32_e32 v115, v147, v147
	v_fmac_f32_e32 v114, v144, v144
	v_fmac_f32_e32 v115, v146, v146
	v_mul_f32_e32 v113, v191, v191
	v_add_f32_e32 v114, v114, v115
	v_mul_f32_e32 v115, v117, v117
	v_mul_f32_e32 v112, v189, v189
	v_fmac_f32_e32 v113, v190, v190
	v_fmac_f32_e32 v115, v116, v116
	v_mul_f32_e32 v116, v119, v119
	v_fmac_f32_e32 v112, v188, v188
	v_add_f32_e32 v113, v113, v114
	v_mul_f32_e32 v114, v139, v139
	v_fmac_f32_e32 v116, v118, v118
	v_add_f32_e32 v112, v112, v113
	v_mul_f32_e32 v113, v137, v137
	v_fmac_f32_e32 v114, v138, v138
	v_add_f32_e32 v115, v115, v116
	v_fmac_f32_e32 v113, v136, v136
	v_add_f32_e32 v114, v114, v115
	v_add_f32_e32 v113, v113, v114
	v_add_f32_e32 v112, v112, v113
	v_mov_b32_e32 v113, v112
	s_nop 1
	v_permlane16_swap_b32_e32 v112, v113
	v_add_f32_e32 v112, v112, v113
	v_mov_b32_e32 v113, v112
	s_nop 1
	v_permlane32_swap_b32_e32 v112, v113
	s_and_saveexec_b64 s[24:25], vcc
	s_cbranch_execz .LBB0_1114
	v_lshl_add_u64 v[114:115], v[236:237], 2, s[8:9]
	v_add_f32_e32 v112, v112, v113
	global_atomic_add_f32 v[114:115], v112, off

.LBB0_1276:
	v_mov_b32_e32 v128, v194
	v_mov_b32_e32 v129, v195
	s_lshl_b32 s16, s43, 8
	s_add_i32 s16, s16, s31
	v_add_u32_e32 v128, s16, v128
	s_lshl_b32 s16, s42, 8
	s_or_b32 s16, s16, s34
	v_lshl_add_u32 v130, v129, 3, s16
	v_ashrrev_i32_e32 v131, 31, v130
	v_ashrrev_i32_e32 v129, 31, v128
	v_lshl_add_u64 v[132:133], v[130:131], 1, s[58:59]
	v_lshlrev_b64 v[134:135], 11, v[128:129]
	v_add_u32_e32 v228, 16, v128
	v_lshl_add_u64 v[134:135], v[132:133], 0, v[134:135]
	v_ashrrev_i32_e32 v229, 31, v228
	global_load_dwordx4 v[200:203], v[134:135], off nt
	global_load_dwordx4 v[204:207], v[134:135], off offset:256 nt
	v_lshlrev_b64 v[134:135], 11, v[228:229]
	v_lshl_add_u64 v[134:135], v[132:133], 0, v[134:135]
	global_load_dwordx4 v[208:211], v[134:135], off nt
	v_add_u32_e32 v192, 32, v128
	v_ashrrev_i32_e32 v193, 31, v192
	global_load_dwordx4 v[212:215], v[134:135], off offset:256 nt
	v_lshlrev_b64 v[182:183], 2, v[130:131]
	v_lshlrev_b64 v[130:131], 11, v[192:193]
	v_lshl_add_u64 v[130:131], v[132:133], 0, v[130:131]
	global_load_dwordx4 v[216:219], v[130:131], off nt
	v_add_u32_e32 v190, 48, v128
	v_add_u32_e32 v188, 0x80, v128
	v_add_u32_e32 v186, 0x90, v128
	v_add_u32_e32 v184, 0xa0, v128
	v_add_u32_e32 v180, 0xb0, v128
	v_ashrrev_i32_e32 v191, 31, v190
	v_ashrrev_i32_e32 v189, 31, v188
	v_ashrrev_i32_e32 v187, 31, v186
	v_ashrrev_i32_e32 v185, 31, v184
	v_ashrrev_i32_e32 v181, 31, v180
	v_lshlrev_b64 v[128:129], 12, v[128:129]
	v_lshlrev_b64 v[134:135], 11, v[190:191]
	v_lshlrev_b64 v[136:137], 11, v[188:189]
	v_lshlrev_b64 v[138:139], 11, v[186:187]
	v_lshlrev_b64 v[140:141], 11, v[184:185]
	v_lshlrev_b64 v[142:143], 11, v[180:181]
	v_lshl_add_u64 v[128:129], s[6:7], 0, v[128:129]
	v_lshl_add_u64 v[134:135], v[132:133], 0, v[134:135]
	v_lshl_add_u64 v[136:137], v[132:133], 0, v[136:137]
	v_lshl_add_u64 v[138:139], v[132:133], 0, v[138:139]
	v_lshl_add_u64 v[230:231], v[132:133], 0, v[140:141]
	v_lshl_add_u64 v[232:233], v[132:133], 0, v[142:143]
	v_lshl_add_u64 v[234:235], v[128:129], 0, v[182:183]
	global_load_dwordx4 v[220:223], v[130:131], off offset:256 nt
	global_load_dwordx4 v[224:227], v[134:135], off nt
	global_load_dwordx4 v[160:163], v[134:135], off offset:256 nt
	global_load_dwordx4 v[156:159], v[136:137], off nt
	global_load_dwordx4 v[152:155], v[136:137], off offset:256 nt
	global_load_dwordx4 v[148:151], v[138:139], off nt
	global_load_dwordx4 v[144:147], v[138:139], off offset:256 nt
	global_load_dwordx4 v[140:143], v[230:231], off nt
	s_nop 0
	global_load_dwordx4 v[136:139], v[230:231], off offset:256 nt
	global_load_dwordx4 v[132:135], v[232:233], off nt
	global_load_dwordx4 v[128:131], v[232:233], off offset:256 nt
	s_and_b64 vcc, exec, s[0:1]
	s_mov_b64 s[0:1], -1
	s_waitcnt vmcnt(0)
	v_lshlrev_b32_e32 v230, 16, v200
	v_and_b32_e32 v231, 0xffff0000, v200
	v_lshlrev_b32_e32 v200, 16, v201
	v_and_b32_e32 v201, 0xffff0000, v201
	v_lshlrev_b32_e32 v238, 16, v206
	v_and_b32_e32 v239, 0xffff0000, v206
	v_lshlrev_b32_e32 v232, 16, v202
	v_and_b32_e32 v233, 0xffff0000, v202
	v_lshlrev_b32_e32 v202, 16, v203
	v_and_b32_e32 v203, 0xffff0000, v203
	v_lshlrev_b32_e32 v236, 16, v204
	v_and_b32_e32 v237, 0xffff0000, v204
	v_lshlrev_b32_e32 v204, 16, v205
	v_and_b32_e32 v205, 0xffff0000, v205
	v_lshlrev_b32_e32 v206, 16, v207
	v_and_b32_e32 v207, 0xffff0000, v207
	v_pk_add_f32 v[126:127], v[126:127], v[200:201]
	v_pk_add_f32 v[124:125], v[124:125], v[230:231]
	v_pk_add_f32 v[108:109], v[108:109], v[238:239]
	v_pk_add_f32 v[122:123], v[122:123], v[202:203]
	v_pk_add_f32 v[120:121], v[120:121], v[232:233]
	v_pk_add_f32 v[118:119], v[118:119], v[204:205]
	v_pk_add_f32 v[116:117], v[116:117], v[236:237]
	v_pk_add_f32 v[110:111], v[110:111], v[206:207]
	global_store_dwordx4 v[234:235], v[124:127], off nt
	global_store_dwordx4 v[234:235], v[120:123], off offset:16 nt
	global_store_dwordx4 v[234:235], v[116:119], off offset:512 nt
	global_store_dwordx4 v[234:235], v[108:111], off offset:528 nt
	s_nop 0
	v_lshlrev_b32_e32 v116, 16, v210
	v_lshlrev_b32_e32 v108, 16, v208
	v_and_b32_e32 v109, 0xffff0000, v208
	v_pk_add_f32 v[108:109], v[112:113], v[108:109]
	v_lshlrev_b64 v[112:113], 12, v[228:229]
	v_lshlrev_b32_e32 v110, 16, v209
	v_and_b32_e32 v111, 0xffff0000, v209
	v_and_b32_e32 v117, 0xffff0000, v210
	v_lshlrev_b32_e32 v118, 16, v211
	v_and_b32_e32 v119, 0xffff0000, v211
	v_lshl_add_u64 v[112:113], s[6:7], 0, v[112:113]
	v_pk_add_f32 v[110:111], v[114:115], v[110:111]
	v_pk_add_f32 v[106:107], v[106:107], v[118:119]
	v_pk_add_f32 v[104:105], v[104:105], v[116:117]
	v_lshl_add_u64 v[112:113], v[112:113], 0, v[182:183]
	global_store_dwordx4 v[112:113], v[108:111], off nt
	global_store_dwordx4 v[112:113], v[104:107], off offset:16 nt
	s_nop 0
	v_lshlrev_b32_e32 v108, 16, v214
	v_lshlrev_b32_e32 v104, 16, v212
	v_and_b32_e32 v105, 0xffff0000, v212
	v_lshlrev_b32_e32 v106, 16, v213
	v_and_b32_e32 v107, 0xffff0000, v213
	v_and_b32_e32 v109, 0xffff0000, v214
	v_lshlrev_b32_e32 v110, 16, v215
	v_and_b32_e32 v111, 0xffff0000, v215
	v_pk_add_f32 v[102:103], v[102:103], v[106:107]
	v_pk_add_f32 v[100:101], v[100:101], v[104:105]
	v_pk_add_f32 v[92:93], v[92:93], v[108:109]
	v_pk_add_f32 v[94:95], v[94:95], v[110:111]
	global_store_dwordx4 v[112:113], v[100:103], off offset:512 nt
	global_store_dwordx4 v[112:113], v[92:95], off offset:528 nt
	s_nop 0
	v_lshlrev_b32_e32 v100, 16, v218
	v_lshlrev_b32_e32 v92, 16, v216
	v_and_b32_e32 v93, 0xffff0000, v216
	v_pk_add_f32 v[92:93], v[96:97], v[92:93]
	v_lshlrev_b64 v[96:97], 12, v[192:193]
	v_lshlrev_b32_e32 v94, 16, v217
	v_and_b32_e32 v95, 0xffff0000, v217
	v_and_b32_e32 v101, 0xffff0000, v218
	v_lshlrev_b32_e32 v102, 16, v219
	v_and_b32_e32 v103, 0xffff0000, v219
	v_lshl_add_u64 v[96:97], s[6:7], 0, v[96:97]
	v_pk_add_f32 v[94:95], v[98:99], v[94:95]
	v_pk_add_f32 v[90:91], v[90:91], v[102:103]
	v_pk_add_f32 v[88:89], v[88:89], v[100:101]
	v_lshl_add_u64 v[96:97], v[96:97], 0, v[182:183]
	global_store_dwordx4 v[96:97], v[92:95], off nt
	global_store_dwordx4 v[96:97], v[88:91], off offset:16 nt
	s_nop 0
	v_lshlrev_b32_e32 v92, 16, v222
	v_lshlrev_b32_e32 v88, 16, v220
	v_and_b32_e32 v89, 0xffff0000, v220
	v_lshlrev_b32_e32 v90, 16, v221
	v_and_b32_e32 v91, 0xffff0000, v221
	v_and_b32_e32 v93, 0xffff0000, v222
	v_lshlrev_b32_e32 v94, 16, v223
	v_and_b32_e32 v95, 0xffff0000, v223
	v_pk_add_f32 v[86:87], v[86:87], v[90:91]
	v_pk_add_f32 v[84:85], v[84:85], v[88:89]
	v_pk_add_f32 v[76:77], v[76:77], v[92:93]
	v_pk_add_f32 v[78:79], v[78:79], v[94:95]
	global_store_dwordx4 v[96:97], v[84:87], off offset:512 nt
	global_store_dwordx4 v[96:97], v[76:79], off offset:528 nt
	s_nop 0
	v_lshlrev_b32_e32 v84, 16, v226
	v_lshlrev_b32_e32 v76, 16, v224
	v_and_b32_e32 v77, 0xffff0000, v224
	v_pk_add_f32 v[76:77], v[80:81], v[76:77]
	v_lshlrev_b64 v[80:81], 12, v[190:191]
	v_lshlrev_b32_e32 v78, 16, v225
	v_and_b32_e32 v79, 0xffff0000, v225
	v_and_b32_e32 v85, 0xffff0000, v226
	v_lshlrev_b32_e32 v86, 16, v227
	v_and_b32_e32 v87, 0xffff0000, v227
	v_lshl_add_u64 v[80:81], s[6:7], 0, v[80:81]
	v_pk_add_f32 v[78:79], v[82:83], v[78:79]
	v_pk_add_f32 v[74:75], v[74:75], v[86:87]
	v_pk_add_f32 v[72:73], v[72:73], v[84:85]
	v_lshl_add_u64 v[80:81], v[80:81], 0, v[182:183]
	global_store_dwordx4 v[80:81], v[76:79], off nt
	global_store_dwordx4 v[80:81], v[72:75], off offset:16 nt
	s_nop 0
	v_lshlrev_b32_e32 v76, 16, v162
	v_lshlrev_b32_e32 v72, 16, v160
	v_and_b32_e32 v73, 0xffff0000, v160
	v_lshlrev_b32_e32 v74, 16, v161
	v_and_b32_e32 v75, 0xffff0000, v161
	v_and_b32_e32 v77, 0xffff0000, v162
	v_lshlrev_b32_e32 v78, 16, v163
	v_and_b32_e32 v79, 0xffff0000, v163
	v_pk_add_f32 v[70:71], v[70:71], v[74:75]
	v_pk_add_f32 v[68:69], v[68:69], v[72:73]
	v_pk_add_f32 v[64:65], v[64:65], v[76:77]
	v_pk_add_f32 v[66:67], v[66:67], v[78:79]
	global_store_dwordx4 v[80:81], v[68:71], off offset:512 nt
	global_store_dwordx4 v[80:81], v[64:67], off offset:528 nt
	s_nop 0
	v_lshlrev_b32_e32 v68, 16, v158
	v_lshlrev_b32_e32 v64, 16, v156
	v_and_b32_e32 v65, 0xffff0000, v156
	v_pk_add_f32 v[60:61], v[60:61], v[64:65]
	v_lshlrev_b64 v[64:65], 12, v[188:189]
	v_lshlrev_b32_e32 v66, 16, v157
	v_and_b32_e32 v67, 0xffff0000, v157
	v_and_b32_e32 v69, 0xffff0000, v158
	v_lshlrev_b32_e32 v70, 16, v159
	v_and_b32_e32 v71, 0xffff0000, v159
	v_lshl_add_u64 v[64:65], s[6:7], 0, v[64:65]
	v_pk_add_f32 v[62:63], v[62:63], v[66:67]
	v_pk_add_f32 v[58:59], v[58:59], v[70:71]
	v_pk_add_f32 v[56:57], v[56:57], v[68:69]
	v_lshl_add_u64 v[64:65], v[64:65], 0, v[182:183]
	global_store_dwordx4 v[64:65], v[60:63], off nt
	global_store_dwordx4 v[64:65], v[56:59], off offset:16 nt
	s_nop 0
	v_lshlrev_b32_e32 v60, 16, v154
	v_lshlrev_b32_e32 v56, 16, v152
	v_and_b32_e32 v57, 0xffff0000, v152
	v_lshlrev_b32_e32 v58, 16, v153
	v_and_b32_e32 v59, 0xffff0000, v153
	v_and_b32_e32 v61, 0xffff0000, v154
	v_lshlrev_b32_e32 v62, 16, v155
	v_and_b32_e32 v63, 0xffff0000, v155
	v_pk_add_f32 v[54:55], v[54:55], v[58:59]
	v_pk_add_f32 v[52:53], v[52:53], v[56:57]
	v_pk_add_f32 v[44:45], v[44:45], v[60:61]
	v_pk_add_f32 v[46:47], v[46:47], v[62:63]
	global_store_dwordx4 v[64:65], v[52:55], off offset:512 nt
	global_store_dwordx4 v[64:65], v[44:47], off offset:528 nt
	s_nop 0
	v_lshlrev_b32_e32 v52, 16, v150
	v_lshlrev_b32_e32 v44, 16, v148
	v_and_b32_e32 v45, 0xffff0000, v148
	v_pk_add_f32 v[44:45], v[48:49], v[44:45]
	v_lshlrev_b64 v[48:49], 12, v[186:187]
	v_lshlrev_b32_e32 v46, 16, v149
	v_and_b32_e32 v47, 0xffff0000, v149
	v_and_b32_e32 v53, 0xffff0000, v150
	v_lshlrev_b32_e32 v54, 16, v151
	v_and_b32_e32 v55, 0xffff0000, v151
	v_lshl_add_u64 v[48:49], s[6:7], 0, v[48:49]
	v_pk_add_f32 v[46:47], v[50:51], v[46:47]
	v_pk_add_f32 v[42:43], v[42:43], v[54:55]
	v_pk_add_f32 v[40:41], v[40:41], v[52:53]
	v_lshl_add_u64 v[48:49], v[48:49], 0, v[182:183]
	global_store_dwordx4 v[48:49], v[44:47], off nt
	global_store_dwordx4 v[48:49], v[40:43], off offset:16 nt
	s_nop 0
	v_lshlrev_b32_e32 v44, 16, v146
	v_lshlrev_b32_e32 v40, 16, v144
	v_and_b32_e32 v41, 0xffff0000, v144
	v_lshlrev_b32_e32 v42, 16, v145
	v_and_b32_e32 v43, 0xffff0000, v145
	v_and_b32_e32 v45, 0xffff0000, v146
	v_lshlrev_b32_e32 v46, 16, v147
	v_and_b32_e32 v47, 0xffff0000, v147
	v_pk_add_f32 v[38:39], v[38:39], v[42:43]
	v_pk_add_f32 v[36:37], v[36:37], v[40:41]
	v_pk_add_f32 v[28:29], v[28:29], v[44:45]
	v_pk_add_f32 v[30:31], v[30:31], v[46:47]
	global_store_dwordx4 v[48:49], v[36:39], off offset:512 nt
	global_store_dwordx4 v[48:49], v[28:31], off offset:528 nt
	s_nop 0
	v_lshlrev_b32_e32 v36, 16, v142
	v_lshlrev_b32_e32 v28, 16, v140
	v_and_b32_e32 v29, 0xffff0000, v140
	v_pk_add_f32 v[28:29], v[32:33], v[28:29]
	v_lshlrev_b64 v[32:33], 12, v[184:185]
	v_lshlrev_b32_e32 v30, 16, v141
	v_and_b32_e32 v31, 0xffff0000, v141
	v_and_b32_e32 v37, 0xffff0000, v142
	v_lshlrev_b32_e32 v38, 16, v143
	v_and_b32_e32 v39, 0xffff0000, v143
	v_lshl_add_u64 v[32:33], s[6:7], 0, v[32:33]
	v_pk_add_f32 v[30:31], v[34:35], v[30:31]
	v_pk_add_f32 v[26:27], v[26:27], v[38:39]
	v_pk_add_f32 v[24:25], v[24:25], v[36:37]
	v_lshl_add_u64 v[32:33], v[32:33], 0, v[182:183]
	global_store_dwordx4 v[32:33], v[28:31], off nt
	global_store_dwordx4 v[32:33], v[24:27], off offset:16 nt
	s_nop 0
	v_lshlrev_b32_e32 v28, 16, v138
	v_lshlrev_b32_e32 v24, 16, v136
	v_and_b32_e32 v25, 0xffff0000, v136
	v_lshlrev_b32_e32 v26, 16, v137
	v_and_b32_e32 v27, 0xffff0000, v137
	v_and_b32_e32 v29, 0xffff0000, v138
	v_lshlrev_b32_e32 v30, 16, v139
	v_and_b32_e32 v31, 0xffff0000, v139
	v_pk_add_f32 v[22:23], v[22:23], v[26:27]
	v_pk_add_f32 v[20:21], v[20:21], v[24:25]
	v_pk_add_f32 v[12:13], v[12:13], v[28:29]
	v_pk_add_f32 v[14:15], v[14:15], v[30:31]
	global_store_dwordx4 v[32:33], v[20:23], off offset:512 nt
	global_store_dwordx4 v[32:33], v[12:15], off offset:528 nt
	s_nop 0
	v_lshlrev_b32_e32 v20, 16, v134
	v_lshlrev_b32_e32 v12, 16, v132
	v_and_b32_e32 v13, 0xffff0000, v132
	v_pk_add_f32 v[12:13], v[16:17], v[12:13]
	v_lshlrev_b64 v[16:17], 12, v[180:181]
	v_lshlrev_b32_e32 v14, 16, v133
	v_and_b32_e32 v15, 0xffff0000, v133
	v_and_b32_e32 v21, 0xffff0000, v134
	v_lshlrev_b32_e32 v22, 16, v135
	v_and_b32_e32 v23, 0xffff0000, v135
	v_lshl_add_u64 v[16:17], s[6:7], 0, v[16:17]
	v_pk_add_f32 v[14:15], v[18:19], v[14:15]
	v_pk_add_f32 v[10:11], v[10:11], v[22:23]
	v_pk_add_f32 v[8:9], v[8:9], v[20:21]
	v_lshl_add_u64 v[16:17], v[16:17], 0, v[182:183]
	global_store_dwordx4 v[16:17], v[12:15], off nt
	global_store_dwordx4 v[16:17], v[8:11], off offset:16 nt
	s_nop 0
	v_lshlrev_b32_e32 v12, 16, v130
	v_lshlrev_b32_e32 v8, 16, v128
	v_and_b32_e32 v9, 0xffff0000, v128
	v_lshlrev_b32_e32 v10, 16, v129
	v_and_b32_e32 v11, 0xffff0000, v129
	v_and_b32_e32 v13, 0xffff0000, v130
	v_lshlrev_b32_e32 v14, 16, v131
	v_and_b32_e32 v15, 0xffff0000, v131
	v_pk_add_f32 v[6:7], v[6:7], v[10:11]
	v_pk_add_f32 v[4:5], v[4:5], v[8:9]
	v_pk_add_f32 v[2:3], v[2:3], v[14:15]
	v_pk_add_f32 v[0:1], v[0:1], v[12:13]
	global_store_dwordx4 v[16:17], v[4:7], off offset:512 nt
	global_store_dwordx4 v[16:17], v[0:3], off offset:528 nt
	s_cbranch_vccnz .LBB0_1261
	s_andn2_b64 vcc, exec, s[8:9]
	s_cbranch_vccnz .LBB0_1260
	s_barrier
	s_branch .LBB0_1260
